# GEMM main loops: LDS-DMA tile loads use SGPR base + 32-bit VGPR offset (24 v_lshl_add_u64 per iteration set removed)
# speedup vs baseline: 1.0024x; 1.0004x over previous
; #define PG8_STAGE(bufoff, gbase, voff) do { _Pragma("unroll") for (int _i = 0; _i < 2; ++_i) \
;         __builtin_amdgcn_global_load_lds((const unsigned*)((const char*)(gbase) + (voff)[_i]), (LAS unsigned*)(lds + (bufoff) + ldsw + _i * 8192), 16, 0, 0); } while (0)
; #define PG8_LDA(dst, b, h) do { _Pragma("unroll") for (int m = 0; m < 4; ++m) _Pragma("unroll") for (int k = 0; k < 2; ++k) dst[m][k] = *(const LAS bf16x8*)(lds + PG8_SA(b, h) + aoff + m * 2048 + k * 1024); } while (0)
; #define PG8_LDB(dst, b, h) do { _Pragma("unroll") for (int n = 0; n < 2; ++n) _Pragma("unroll") for (int k = 0; k < 2; ++k) dst[n][k] = *(const LAS bf16x8*)(lds + PG8_SB(b, h) + boff + n * 2048 + k * 1024); } while (0)
; #define PG8_WAIT_V(n) asm volatile("s_waitcnt vmcnt(" #n ")" ::: "memory")
; #define PG8_WAIT_L(n) asm volatile("s_waitcnt lgkmcnt(" #n ")" ::: "memory")
; template <class Epi>
; DI void gemm_phase(LAS unsigned char* lds, int tid, const Gemm g, const Order& S, const Epi& E) {
;     ...
;         for (int t = 0; t < nt; t += 2) {
;             const bool last = (t == nt - 2);
;             const char* a1 = cA + (size_t)(t + 1) * kstep;
;             const char* a2 = last ? nA : cA + (size_t)(t + 2) * kstep; const char* b2 = last ? nB : cB + (size_t)(t + 2) * kstep;
;             const char* a3 = a2 + kstep; const char* b3 = b2 + kstep;
;             PG8_LDB(B0, 0, 0); PG8_LDB(B1, 0, 1); PG8_SCHED; PG8_LDA(At, 0, 0); PG8_STAGE(PG8_SA(1, 1), a1 + hstepA, voffA);
;             PG8_WAIT_V(8); PG8_WAIT_L(0); PG8_BAR; PG8_MMA(0, 0, At, B0); PG8_MMA(0, 1, At, B1); PG8_BAR; PG8_SCHED;
;             PG8_LDA(At, 0, 1); PG8_STAGE(PG8_SB(0, 0), b2, voffB); PG8_STAGE(PG8_SB(0, 1), b2 + hstepB, voffB); PG8_STAGE(PG8_SA(0, 0), a2, voffA);
;             PG8_WAIT_V(8); PG8_WAIT_L(0); PG8_BAR; PG8_MMA(1, 0, At, B0); PG8_MMA(1, 1, At, B1); PG8_BAR; PG8_SCHED;
;             PG8_LDB(B0, 1, 0); PG8_LDB(B1, 1, 1); PG8_SCHED; PG8_LDA(At, 1, 0); PG8_STAGE(PG8_SA(0, 1), a2 + hstepA, voffA);
;             PG8_WAIT_V(8); PG8_WAIT_L(0); PG8_BAR; PG8_MMA(0, 0, At, B0); PG8_MMA(0, 1, At, B1); PG8_BAR; PG8_SCHED;
;             PG8_LDA(At, 1, 1); PG8_STAGE(PG8_SB(1, 0), b3, voffB); PG8_STAGE(PG8_SB(1, 1), b3 + hstepB, voffB); PG8_STAGE(PG8_SA(1, 0), a3, voffA);
;             PG8_WAIT_V(8); PG8_WAIT_L(0); PG8_BAR; PG8_MMA(1, 0, At, B0); PG8_MMA(1, 1, At, B1); PG8_BAR; PG8_SCHED;
.LBB0_387:
	s_add_u32 s12, s8, 0xfffc0080
	s_addc_u32 s13, s9, -1
	s_add_i32 s29, 0, 0x10000
	s_cmp_eq_u32 s81, 12
	s_cselect_b32 s91, s20, s13
	s_cselect_b32 s90, s33, s12
	v_add_u32_e32 v0, s29, v171
	s_cselect_b32 s89, s52, s79
	s_cselect_b32 s88, s53, s77
	s_add_i32 s12, 0, 0x14000
	ds_read_b128 v[174:177], v0
	ds_read_b128 v[196:199], v0 offset:1024
	ds_read_b128 v[200:203], v0 offset:2048
	ds_read_b128 v[204:207], v0 offset:3072
	v_add_u32_e32 v0, s12, v171
	ds_read_b128 v[208:211], v0
	ds_read_b128 v[212:215], v0 offset:1024
	ds_read_b128 v[216:219], v0 offset:2048
	ds_read_b128 v[220:223], v0 offset:3072
	s_add_i32 m0, s83, 0xc000
	ds_read_b128 v[224:227], v172
	ds_read_b128 v[228:231], v172 offset:1024
	ds_read_b128 v[232:235], v172 offset:2048
	ds_read_b128 v[236:239], v172 offset:3072
	ds_read_b128 v[240:243], v172 offset:4096
	ds_read_b128 v[244:247], v172 offset:5120
	ds_read_b128 v[248:251], v172 offset:6144
	ds_read_b128 v[188:191], v172 offset:7168
	global_load_lds_dwordx4 v138, s[8:9]
	s_add_i32 m0, s83, 0xe000
	s_nop 0
	global_load_lds_dwordx4 v140, s[8:9]
	s_waitcnt vmcnt(8)
	s_waitcnt lgkmcnt(0)
	s_barrier
	s_setprio 1
	s_waitcnt lgkmcnt(0)
	v_mfma_f32_16x16x32_bf16 v[126:129], v[174:177], v[224:227], v[126:129]
	v_mfma_f32_16x16x32_bf16 v[122:125], v[200:203], v[224:227], v[122:125]
	v_mfma_f32_16x16x32_bf16 v[118:121], v[174:177], v[232:235], v[118:121]
	v_mfma_f32_16x16x32_bf16 v[114:117], v[200:203], v[232:235], v[114:117]
	v_mfma_f32_16x16x32_bf16 v[102:105], v[174:177], v[240:243], v[102:105]
	v_mfma_f32_16x16x32_bf16 v[98:101], v[200:203], v[240:243], v[98:101]
	v_mfma_f32_16x16x32_bf16 v[86:89], v[174:177], v[248:251], v[86:89]
	v_mfma_f32_16x16x32_bf16 v[82:85], v[200:203], v[248:251], v[82:85]
	v_mfma_f32_16x16x32_bf16 v[126:129], v[196:199], v[228:231], v[126:129]
	v_mfma_f32_16x16x32_bf16 v[122:125], v[204:207], v[228:231], v[122:125]
	v_mfma_f32_16x16x32_bf16 v[118:121], v[196:199], v[236:239], v[118:121]
	v_mfma_f32_16x16x32_bf16 v[114:117], v[204:207], v[236:239], v[114:117]
	v_mfma_f32_16x16x32_bf16 v[102:105], v[196:199], v[244:247], v[102:105]
	v_mfma_f32_16x16x32_bf16 v[98:101], v[204:207], v[244:247], v[98:101]
	v_mfma_f32_16x16x32_bf16 v[86:89], v[196:199], v[188:191], v[86:89]
	v_mfma_f32_16x16x32_bf16 v[82:85], v[204:207], v[188:191], v[82:85]
	s_setprio 0
	s_setprio 1
	v_mfma_f32_16x16x32_bf16 v[110:113], v[208:211], v[224:227], v[110:113]
	v_mfma_f32_16x16x32_bf16 v[106:109], v[216:219], v[224:227], v[106:109]
	v_mfma_f32_16x16x32_bf16 v[94:97], v[208:211], v[232:235], v[94:97]
	v_mfma_f32_16x16x32_bf16 v[90:93], v[216:219], v[232:235], v[90:93]
	v_mfma_f32_16x16x32_bf16 v[78:81], v[208:211], v[240:243], v[78:81]
	v_mfma_f32_16x16x32_bf16 v[74:77], v[216:219], v[240:243], v[74:77]
	v_mfma_f32_16x16x32_bf16 v[70:73], v[208:211], v[248:251], v[70:73]
	v_mfma_f32_16x16x32_bf16 v[66:69], v[216:219], v[248:251], v[66:69]
	v_mfma_f32_16x16x32_bf16 v[110:113], v[212:215], v[228:231], v[110:113]
	v_mfma_f32_16x16x32_bf16 v[106:109], v[220:223], v[228:231], v[106:109]
	v_mfma_f32_16x16x32_bf16 v[94:97], v[212:215], v[236:239], v[94:97]
	v_mfma_f32_16x16x32_bf16 v[90:93], v[220:223], v[236:239], v[90:93]
	v_mfma_f32_16x16x32_bf16 v[78:81], v[212:215], v[244:247], v[78:81]
	v_mfma_f32_16x16x32_bf16 v[74:77], v[220:223], v[244:247], v[74:77]
	v_mfma_f32_16x16x32_bf16 v[70:73], v[212:215], v[188:191], v[70:73]
	v_mfma_f32_16x16x32_bf16 v[66:69], v[220:223], v[188:191], v[66:69]
	s_setprio 0
	s_barrier
	s_add_i32 s13, s29, s97
	v_lshl_add_u64 v[160:161], s[88:89], 0, v[132:133]
	s_mov_b32 m0, s13
	ds_read_b128 v[188:191], v172 offset:16384
	ds_read_b128 v[224:227], v172 offset:17408
	ds_read_b128 v[228:231], v172 offset:18432
	ds_read_b128 v[232:235], v172 offset:19456
	ds_read_b128 v[236:239], v172 offset:20480
	ds_read_b128 v[240:243], v172 offset:21504
	ds_read_b128 v[244:247], v172 offset:22528
	ds_read_b128 v[248:251], v172 offset:23552
	global_load_lds_dwordx4 v132, s[88:89]
	s_add_i32 m0, s13, 0x2000
	s_add_u32 s92, s88, 0x40000
	v_lshl_add_u64 v[166:167], s[88:89], 0, v[136:137]
	s_addc_u32 s93, s89, 0
	s_add_i32 s12, s12, s97
	global_load_lds_dwordx4 v136, s[88:89]
	s_mov_b32 m0, s12
	v_lshl_add_u64 v[252:253], s[90:91], 0, v[134:135]
	global_load_lds_dwordx4 v132, s[92:93]
	s_add_i32 m0, s12, 0x2000
	s_nop 0
	global_load_lds_dwordx4 v136, s[92:93]
	v_lshl_add_u64 v[178:179], s[90:91], 0, v[130:131]
	s_mov_b32 m0, s83
	s_nop 0
	global_load_lds_dwordx4 v130, s[90:91]
	s_mov_b32 m0, s45
	s_nop 0
	global_load_lds_dwordx4 v134, s[90:91]
	s_waitcnt vmcnt(8)
	s_waitcnt lgkmcnt(0)
	s_barrier
; #define PG8_STAGE(bufoff, gbase, voff) do { _Pragma("unroll") for (int _i = 0; _i < 2; ++_i) \
;         __builtin_amdgcn_global_load_lds((const unsigned*)((const char*)(gbase) + (voff)[_i]), (LAS unsigned*)(lds + (bufoff) + ldsw + _i * 8192), 16, 0, 0); } while (0)
; #define PG8_LDA(dst, b, h) do { _Pragma("unroll") for (int m = 0; m < 4; ++m) _Pragma("unroll") for (int k = 0; k < 2; ++k) dst[m][k] = *(const LAS bf16x8*)(lds + PG8_SA(b, h) + aoff + m * 2048 + k * 1024); } while (0)
; #define PG8_LDB(dst, b, h) do { _Pragma("unroll") for (int n = 0; n < 2; ++n) _Pragma("unroll") for (int k = 0; k < 2; ++k) dst[n][k] = *(const LAS bf16x8*)(lds + PG8_SB(b, h) + boff + n * 2048 + k * 1024); } while (0)
; #define PG8_WAIT_V(n) asm volatile("s_waitcnt vmcnt(" #n ")" ::: "memory")
; #define PG8_WAIT_L(n) asm volatile("s_waitcnt lgkmcnt(" #n ")" ::: "memory")
; template <class Epi>
; DI void gemm_phase(LAS unsigned char* lds, int tid, const Gemm g, const Order& S, const Epi& E) {
;     ...
;         for (int t = 0; t < nt; t += 2) {
;             const bool last = (t == nt - 2);
;             const char* a1 = cA + (size_t)(t + 1) * kstep;
;             const char* a2 = last ? nA : cA + (size_t)(t + 2) * kstep; const char* b2 = last ? nB : cB + (size_t)(t + 2) * kstep;
;             const char* a3 = a2 + kstep; const char* b3 = b2 + kstep;
;             PG8_LDB(B0, 0, 0); PG8_LDB(B1, 0, 1); PG8_SCHED; PG8_LDA(At, 0, 0); PG8_STAGE(PG8_SA(1, 1), a1 + hstepA, voffA);
;             PG8_WAIT_V(8); PG8_WAIT_L(0); PG8_BAR; PG8_MMA(0, 0, At, B0); PG8_MMA(0, 1, At, B1); PG8_BAR; PG8_SCHED;
;             PG8_LDA(At, 0, 1); PG8_STAGE(PG8_SB(0, 0), b2, voffB); PG8_STAGE(PG8_SB(0, 1), b2 + hstepB, voffB); PG8_STAGE(PG8_SA(0, 0), a2, voffA);
;             PG8_WAIT_V(8); PG8_WAIT_L(0); PG8_BAR; PG8_MMA(1, 0, At, B0); PG8_MMA(1, 1, At, B1); PG8_BAR; PG8_SCHED;
;             PG8_LDB(B0, 1, 0); PG8_LDB(B1, 1, 1); PG8_SCHED; PG8_LDA(At, 1, 0); PG8_STAGE(PG8_SA(0, 1), a2 + hstepA, voffA);
;             PG8_WAIT_V(8); PG8_WAIT_L(0); PG8_BAR; PG8_MMA(0, 0, At, B0); PG8_MMA(0, 1, At, B1); PG8_BAR; PG8_SCHED;
;             PG8_LDA(At, 1, 1); PG8_STAGE(PG8_SB(1, 0), b3, voffB); PG8_STAGE(PG8_SB(1, 1), b3 + hstepB, voffB); PG8_STAGE(PG8_SA(1, 0), a3, voffA);
;             PG8_WAIT_V(8); PG8_WAIT_L(0); PG8_BAR; PG8_MMA(1, 0, At, B0); PG8_MMA(1, 1, At, B1); PG8_BAR; PG8_SCHED;
	s_setprio 1
	s_waitcnt lgkmcnt(0)
	v_mfma_f32_16x16x32_bf16 v[62:65], v[174:177], v[188:191], v[62:65]
	v_mfma_f32_16x16x32_bf16 v[58:61], v[200:203], v[188:191], v[58:61]
	v_mfma_f32_16x16x32_bf16 v[54:57], v[174:177], v[228:231], v[54:57]
	v_mfma_f32_16x16x32_bf16 v[50:53], v[200:203], v[228:231], v[50:53]
	v_mfma_f32_16x16x32_bf16 v[38:41], v[174:177], v[236:239], v[38:41]
	v_mfma_f32_16x16x32_bf16 v[34:37], v[200:203], v[236:239], v[34:37]
	v_mfma_f32_16x16x32_bf16 v[22:25], v[174:177], v[244:247], v[22:25]
	v_mfma_f32_16x16x32_bf16 v[18:21], v[200:203], v[244:247], v[18:21]
	v_mfma_f32_16x16x32_bf16 v[62:65], v[196:199], v[224:227], v[62:65]
	v_mfma_f32_16x16x32_bf16 v[58:61], v[204:207], v[224:227], v[58:61]
	v_mfma_f32_16x16x32_bf16 v[54:57], v[196:199], v[232:235], v[54:57]
	v_mfma_f32_16x16x32_bf16 v[50:53], v[204:207], v[232:235], v[50:53]
	v_mfma_f32_16x16x32_bf16 v[38:41], v[196:199], v[240:243], v[38:41]
	v_mfma_f32_16x16x32_bf16 v[34:37], v[204:207], v[240:243], v[34:37]
	v_mfma_f32_16x16x32_bf16 v[22:25], v[196:199], v[248:251], v[22:25]
	v_mfma_f32_16x16x32_bf16 v[18:21], v[204:207], v[248:251], v[18:21]
	s_setprio 0
	s_setprio 1
	v_mfma_f32_16x16x32_bf16 v[46:49], v[208:211], v[188:191], v[46:49]
	v_mfma_f32_16x16x32_bf16 v[42:45], v[216:219], v[188:191], v[42:45]
	v_mfma_f32_16x16x32_bf16 v[30:33], v[208:211], v[228:231], v[30:33]
	v_mfma_f32_16x16x32_bf16 v[26:29], v[216:219], v[228:231], v[26:29]
	v_mfma_f32_16x16x32_bf16 v[14:17], v[208:211], v[236:239], v[14:17]
	v_mfma_f32_16x16x32_bf16 v[10:13], v[216:219], v[236:239], v[10:13]
	v_mfma_f32_16x16x32_bf16 v[6:9], v[208:211], v[244:247], v[6:9]
	v_mfma_f32_16x16x32_bf16 v[2:5], v[216:219], v[244:247], v[2:5]
	v_mfma_f32_16x16x32_bf16 v[46:49], v[212:215], v[224:227], v[46:49]
	v_mfma_f32_16x16x32_bf16 v[42:45], v[220:223], v[224:227], v[42:45]
	v_mfma_f32_16x16x32_bf16 v[30:33], v[212:215], v[232:235], v[30:33]
	v_mfma_f32_16x16x32_bf16 v[26:29], v[220:223], v[232:235], v[26:29]
	v_mfma_f32_16x16x32_bf16 v[14:17], v[212:215], v[240:243], v[14:17]
	v_mfma_f32_16x16x32_bf16 v[10:13], v[220:223], v[240:243], v[10:13]
	v_mfma_f32_16x16x32_bf16 v[6:9], v[212:215], v[248:251], v[6:9]
	v_mfma_f32_16x16x32_bf16 v[2:5], v[220:223], v[248:251], v[2:5]
	s_setprio 0
	s_barrier
	s_add_i32 s12, 0, 0x18000
	v_add_u32_e32 v0, s12, v171
	s_add_i32 s13, 0, 0x1c000
	ds_read_b128 v[174:177], v0
	ds_read_b128 v[188:191], v0 offset:1024
	ds_read_b128 v[196:199], v0 offset:2048
	ds_read_b128 v[200:203], v0 offset:3072
	v_add_u32_e32 v0, s13, v171
	ds_read_b128 v[204:207], v0
	ds_read_b128 v[208:211], v0 offset:1024
	ds_read_b128 v[212:215], v0 offset:2048
	ds_read_b128 v[216:219], v0 offset:3072
	s_add_u32 s90, s90, 0x40000
	s_addc_u32 s91, s91, 0
	s_mov_b32 m0, s34
	ds_read_b128 v[220:223], v172 offset:32768
	ds_read_b128 v[224:227], v172 offset:33792
	ds_read_b128 v[228:231], v172 offset:34816
	ds_read_b128 v[232:235], v172 offset:35840
	ds_read_b128 v[236:239], v172 offset:36864
	ds_read_b128 v[240:243], v172 offset:37888
	ds_read_b128 v[244:247], v172 offset:38912
	ds_read_b128 v[248:251], v172 offset:39936
	global_load_lds_dwordx4 v130, s[90:91]
	s_mov_b32 m0, s22
	s_nop 0
	global_load_lds_dwordx4 v134, s[90:91]
	s_waitcnt vmcnt(8)
	s_waitcnt lgkmcnt(0)
	s_barrier
	s_setprio 1
	s_waitcnt lgkmcnt(0)
	v_mfma_f32_16x16x32_bf16 v[126:129], v[174:177], v[220:223], v[126:129]
	v_mfma_f32_16x16x32_bf16 v[122:125], v[196:199], v[220:223], v[122:125]
	v_mfma_f32_16x16x32_bf16 v[118:121], v[174:177], v[228:231], v[118:121]
	v_mfma_f32_16x16x32_bf16 v[114:117], v[196:199], v[228:231], v[114:117]
	v_mfma_f32_16x16x32_bf16 v[102:105], v[174:177], v[236:239], v[102:105]
	v_mfma_f32_16x16x32_bf16 v[98:101], v[196:199], v[236:239], v[98:101]
	v_mfma_f32_16x16x32_bf16 v[86:89], v[174:177], v[244:247], v[86:89]
	v_mfma_f32_16x16x32_bf16 v[82:85], v[196:199], v[244:247], v[82:85]
	v_mfma_f32_16x16x32_bf16 v[126:129], v[188:191], v[224:227], v[126:129]
	v_mfma_f32_16x16x32_bf16 v[122:125], v[200:203], v[224:227], v[122:125]
	v_mfma_f32_16x16x32_bf16 v[118:121], v[188:191], v[232:235], v[118:121]
	v_mfma_f32_16x16x32_bf16 v[114:117], v[200:203], v[232:235], v[114:117]
	v_mfma_f32_16x16x32_bf16 v[102:105], v[188:191], v[240:243], v[102:105]
	v_mfma_f32_16x16x32_bf16 v[98:101], v[200:203], v[240:243], v[98:101]
	v_mfma_f32_16x16x32_bf16 v[86:89], v[188:191], v[248:251], v[86:89]
	v_mfma_f32_16x16x32_bf16 v[82:85], v[200:203], v[248:251], v[82:85]
	s_setprio 0
	s_setprio 1
	v_mfma_f32_16x16x32_bf16 v[110:113], v[204:207], v[220:223], v[110:113]
	v_mfma_f32_16x16x32_bf16 v[106:109], v[212:215], v[220:223], v[106:109]
	v_mfma_f32_16x16x32_bf16 v[94:97], v[204:207], v[228:231], v[94:97]
	v_mfma_f32_16x16x32_bf16 v[90:93], v[212:215], v[228:231], v[90:93]
	v_mfma_f32_16x16x32_bf16 v[78:81], v[204:207], v[236:239], v[78:81]
	v_mfma_f32_16x16x32_bf16 v[74:77], v[212:215], v[236:239], v[74:77]
	v_mfma_f32_16x16x32_bf16 v[70:73], v[204:207], v[244:247], v[70:73]
	v_mfma_f32_16x16x32_bf16 v[66:69], v[212:215], v[244:247], v[66:69]
	v_mfma_f32_16x16x32_bf16 v[110:113], v[208:211], v[224:227], v[110:113]
	v_mfma_f32_16x16x32_bf16 v[106:109], v[216:219], v[224:227], v[106:109]
	v_mfma_f32_16x16x32_bf16 v[94:97], v[208:211], v[232:235], v[94:97]
	v_mfma_f32_16x16x32_bf16 v[90:93], v[216:219], v[232:235], v[90:93]
	v_mfma_f32_16x16x32_bf16 v[78:81], v[208:211], v[240:243], v[78:81]
	v_mfma_f32_16x16x32_bf16 v[74:77], v[216:219], v[240:243], v[74:77]
	v_mfma_f32_16x16x32_bf16 v[70:73], v[208:211], v[248:251], v[70:73]
	v_mfma_f32_16x16x32_bf16 v[66:69], v[216:219], v[248:251], v[66:69]
	s_setprio 0
	s_barrier
; #define PG8_STAGE(bufoff, gbase, voff) do { _Pragma("unroll") for (int _i = 0; _i < 2; ++_i) \
;         __builtin_amdgcn_global_load_lds((const unsigned*)((const char*)(gbase) + (voff)[_i]), (LAS unsigned*)(lds + (bufoff) + ldsw + _i * 8192), 16, 0, 0); } while (0)
; #define PG8_LDA(dst, b, h) do { _Pragma("unroll") for (int m = 0; m < 4; ++m) _Pragma("unroll") for (int k = 0; k < 2; ++k) dst[m][k] = *(const LAS bf16x8*)(lds + PG8_SA(b, h) + aoff + m * 2048 + k * 1024); } while (0)
; #define PG8_LDB(dst, b, h) do { _Pragma("unroll") for (int n = 0; n < 2; ++n) _Pragma("unroll") for (int k = 0; k < 2; ++k) dst[n][k] = *(const LAS bf16x8*)(lds + PG8_SB(b, h) + boff + n * 2048 + k * 1024); } while (0)
; #define PG8_WAIT_V(n) asm volatile("s_waitcnt vmcnt(" #n ")" ::: "memory")
; #define PG8_BAR __builtin_amdgcn_s_barrier()
; template <class Epi>
; DI void gemm_phase(LAS unsigned char* lds, int tid, const Gemm g, const Order& S, const Epi& E) {
;     ...
;         for (int t = 0; t < nt; t += 2) {
;             const bool last = (t == nt - 2);
;             const char* a1 = cA + (size_t)(t + 1) * kstep;
;             const char* a2 = last ? nA : cA + (size_t)(t + 2) * kstep; const char* b2 = last ? nB : cB + (size_t)(t + 2) * kstep;
;             const char* a3 = a2 + kstep; const char* b3 = b2 + kstep;
;             PG8_LDB(B0, 0, 0); PG8_LDB(B1, 0, 1); PG8_SCHED; PG8_LDA(At, 0, 0); PG8_STAGE(PG8_SA(1, 1), a1 + hstepA, voffA);
;             PG8_WAIT_V(8); PG8_WAIT_L(0); PG8_BAR; PG8_MMA(0, 0, At, B0); PG8_MMA(0, 1, At, B1); PG8_BAR; PG8_SCHED;
;             PG8_LDA(At, 0, 1); PG8_STAGE(PG8_SB(0, 0), b2, voffB); PG8_STAGE(PG8_SB(0, 1), b2 + hstepB, voffB); PG8_STAGE(PG8_SA(0, 0), a2, voffA);
;             PG8_WAIT_V(8); PG8_WAIT_L(0); PG8_BAR; PG8_MMA(1, 0, At, B0); PG8_MMA(1, 1, At, B1); PG8_BAR; PG8_SCHED;
;             PG8_LDB(B0, 1, 0); PG8_LDB(B1, 1, 1); PG8_SCHED; PG8_LDA(At, 1, 0); PG8_STAGE(PG8_SA(0, 1), a2 + hstepA, voffA);
;             PG8_WAIT_V(8); PG8_WAIT_L(0); PG8_BAR; PG8_MMA(0, 0, At, B0); PG8_MMA(0, 1, At, B1); PG8_BAR; PG8_SCHED;
;             PG8_LDA(At, 1, 1); PG8_STAGE(PG8_SB(1, 0), b3, voffB); PG8_STAGE(PG8_SB(1, 1), b3 + hstepB, voffB); PG8_STAGE(PG8_SA(1, 0), a3, voffA);
;             PG8_WAIT_V(8); PG8_WAIT_L(0); PG8_BAR; PG8_MMA(1, 0, At, B0); PG8_MMA(1, 1, At, B1); PG8_BAR; PG8_SCHED;
;         }
;         if (wr == 0) PG8_BAR;
	s_add_i32 s12, s12, s97
	v_lshl_add_u64 v[160:161], v[160:161], 0, s[24:25]
	s_mov_b32 m0, s12
	ds_read_b128 v[220:223], v172 offset:49152
	ds_read_b128 v[224:227], v172 offset:50176
	ds_read_b128 v[228:231], v172 offset:51200
	ds_read_b128 v[232:235], v172 offset:52224
	ds_read_b128 v[236:239], v172 offset:53248
	ds_read_b128 v[240:243], v172 offset:54272
	ds_read_b128 v[244:247], v172 offset:55296
	ds_read_b128 v[248:251], v172 offset:56320
	global_load_lds_dwordx4 v[160:161], off
	s_add_i32 m0, s12, 0x2000
	s_add_u32 s88, s88, 0x40080
	v_lshl_add_u64 v[160:161], v[166:167], 0, s[24:25]
	s_addc_u32 s89, s89, 0
	s_add_i32 s12, s13, s97
	global_load_lds_dwordx4 v[160:161], off
	s_mov_b32 m0, s12
	s_nop 0
	global_load_lds_dwordx4 v132, s[88:89]
	s_add_i32 m0, s12, 0x2000
	s_nop 0
	global_load_lds_dwordx4 v136, s[88:89]
	v_lshl_add_u64 v[160:161], v[178:179], 0, s[24:25]
	s_mov_b32 m0, s48
	s_nop 0
	global_load_lds_dwordx4 v[160:161], off
	v_lshl_add_u64 v[160:161], v[252:253], 0, s[24:25]
	s_mov_b32 m0, s40
	s_nop 0
	global_load_lds_dwordx4 v[160:161], off
	s_waitcnt vmcnt(8)
	s_waitcnt lgkmcnt(0)
	s_barrier
	s_setprio 1
	s_waitcnt lgkmcnt(0)
	v_mfma_f32_16x16x32_bf16 v[62:65], v[174:177], v[220:223], v[62:65]
	v_mfma_f32_16x16x32_bf16 v[58:61], v[196:199], v[220:223], v[58:61]
	v_mfma_f32_16x16x32_bf16 v[54:57], v[174:177], v[228:231], v[54:57]
	v_mfma_f32_16x16x32_bf16 v[50:53], v[196:199], v[228:231], v[50:53]
	v_mfma_f32_16x16x32_bf16 v[38:41], v[174:177], v[236:239], v[38:41]
	v_mfma_f32_16x16x32_bf16 v[34:37], v[196:199], v[236:239], v[34:37]
	v_mfma_f32_16x16x32_bf16 v[22:25], v[174:177], v[244:247], v[22:25]
	v_mfma_f32_16x16x32_bf16 v[18:21], v[196:199], v[244:247], v[18:21]
	v_mfma_f32_16x16x32_bf16 v[62:65], v[188:191], v[224:227], v[62:65]
	v_mfma_f32_16x16x32_bf16 v[58:61], v[200:203], v[224:227], v[58:61]
	v_mfma_f32_16x16x32_bf16 v[54:57], v[188:191], v[232:235], v[54:57]
	v_mfma_f32_16x16x32_bf16 v[50:53], v[200:203], v[232:235], v[50:53]
	v_mfma_f32_16x16x32_bf16 v[38:41], v[188:191], v[240:243], v[38:41]
	v_mfma_f32_16x16x32_bf16 v[34:37], v[200:203], v[240:243], v[34:37]
	v_mfma_f32_16x16x32_bf16 v[22:25], v[188:191], v[248:251], v[22:25]
	v_mfma_f32_16x16x32_bf16 v[18:21], v[200:203], v[248:251], v[18:21]
	s_setprio 0
	s_setprio 1
	v_mfma_f32_16x16x32_bf16 v[46:49], v[204:207], v[220:223], v[46:49]
	v_mfma_f32_16x16x32_bf16 v[42:45], v[212:215], v[220:223], v[42:45]
	v_mfma_f32_16x16x32_bf16 v[30:33], v[204:207], v[228:231], v[30:33]
	v_mfma_f32_16x16x32_bf16 v[26:29], v[212:215], v[228:231], v[26:29]
	v_mfma_f32_16x16x32_bf16 v[14:17], v[204:207], v[236:239], v[14:17]
	v_mfma_f32_16x16x32_bf16 v[10:13], v[212:215], v[236:239], v[10:13]
	v_mfma_f32_16x16x32_bf16 v[6:9], v[204:207], v[244:247], v[6:9]
	v_mfma_f32_16x16x32_bf16 v[2:5], v[212:215], v[244:247], v[2:5]
	v_mfma_f32_16x16x32_bf16 v[46:49], v[208:211], v[224:227], v[46:49]
	v_mfma_f32_16x16x32_bf16 v[42:45], v[216:219], v[224:227], v[42:45]
	v_mfma_f32_16x16x32_bf16 v[30:33], v[208:211], v[232:235], v[30:33]
	v_mfma_f32_16x16x32_bf16 v[26:29], v[216:219], v[232:235], v[26:29]
	v_mfma_f32_16x16x32_bf16 v[14:17], v[208:211], v[240:243], v[14:17]
	v_mfma_f32_16x16x32_bf16 v[10:13], v[216:219], v[240:243], v[10:13]
	v_mfma_f32_16x16x32_bf16 v[6:9], v[208:211], v[248:251], v[6:9]
	v_mfma_f32_16x16x32_bf16 v[2:5], v[216:219], v[248:251], v[2:5]
	s_setprio 0
	s_barrier
	s_add_i32 s81, s81, 2
	s_add_u32 s8, s8, 0x100
	s_addc_u32 s9, s9, 0
	s_add_u32 s77, s77, 0x100
	s_addc_u32 s79, s79, 0
	s_cmp_gt_u32 s81, 13
	s_cbranch_scc0 .LBB0_387
	s_and_b64 vcc, exec, s[74:75]
	s_cbranch_vccz .LBB0_390
	s_barrier

; #define PG8_STAGE(bufoff, gbase, voff) do { _Pragma("unroll") for (int _i = 0; _i < 2; ++_i) \
;         __builtin_amdgcn_global_load_lds((const unsigned*)((const char*)(gbase) + (voff)[_i]), (LAS unsigned*)(lds + (bufoff) + ldsw + _i * 8192), 16, 0, 0); } while (0)
; #define PG8_LDA(dst, b, h) do { _Pragma("unroll") for (int m = 0; m < 4; ++m) _Pragma("unroll") for (int k = 0; k < 2; ++k) dst[m][k] = *(const LAS bf16x8*)(lds + PG8_SA(b, h) + aoff + m * 2048 + k * 1024); } while (0)
; #define PG8_LDB(dst, b, h) do { _Pragma("unroll") for (int n = 0; n < 2; ++n) _Pragma("unroll") for (int k = 0; k < 2; ++k) dst[n][k] = *(const LAS bf16x8*)(lds + PG8_SB(b, h) + boff + n * 2048 + k * 1024); } while (0)
; #define PG8_WAIT_V(n) asm volatile("s_waitcnt vmcnt(" #n ")" ::: "memory")
; #define PG8_WAIT_L(n) asm volatile("s_waitcnt lgkmcnt(" #n ")" ::: "memory")
; template <class Epi>
; DI void gemm_phase(LAS unsigned char* lds, int tid, const Gemm g, const Order& S, const Epi& E) {
;     ...
;         for (int t = 0; t < nt; t += 2) {
;             const bool last = (t == nt - 2);
;             const char* a1 = cA + (size_t)(t + 1) * kstep;
;             const char* a2 = last ? nA : cA + (size_t)(t + 2) * kstep; const char* b2 = last ? nB : cB + (size_t)(t + 2) * kstep;
;             const char* a3 = a2 + kstep; const char* b3 = b2 + kstep;
;             PG8_LDB(B0, 0, 0); PG8_LDB(B1, 0, 1); PG8_SCHED; PG8_LDA(At, 0, 0); PG8_STAGE(PG8_SA(1, 1), a1 + hstepA, voffA);
;             PG8_WAIT_V(8); PG8_WAIT_L(0); PG8_BAR; PG8_MMA(0, 0, At, B0); PG8_MMA(0, 1, At, B1); PG8_BAR; PG8_SCHED;
;             PG8_LDA(At, 0, 1); PG8_STAGE(PG8_SB(0, 0), b2, voffB); PG8_STAGE(PG8_SB(0, 1), b2 + hstepB, voffB); PG8_STAGE(PG8_SA(0, 0), a2, voffA);
;             PG8_WAIT_V(8); PG8_WAIT_L(0); PG8_BAR; PG8_MMA(1, 0, At, B0); PG8_MMA(1, 1, At, B1); PG8_BAR; PG8_SCHED;
;             PG8_LDB(B0, 1, 0); PG8_LDB(B1, 1, 1); PG8_SCHED; PG8_LDA(At, 1, 0); PG8_STAGE(PG8_SA(0, 1), a2 + hstepA, voffA);
;             PG8_WAIT_V(8); PG8_WAIT_L(0); PG8_BAR; PG8_MMA(0, 0, At, B0); PG8_MMA(0, 1, At, B1); PG8_BAR; PG8_SCHED;
;             PG8_LDA(At, 1, 1); PG8_STAGE(PG8_SB(1, 0), b3, voffB); PG8_STAGE(PG8_SB(1, 1), b3 + hstepB, voffB); PG8_STAGE(PG8_SA(1, 0), a3, voffA);
;             PG8_WAIT_V(8); PG8_WAIT_L(0); PG8_BAR; PG8_MMA(1, 0, At, B0); PG8_MMA(1, 1, At, B1); PG8_BAR; PG8_SCHED;
.LBB0_466:
	s_add_i32 vcc_hi, s92, 2
	s_add_u32 s94, s90, 0x80
	s_addc_u32 s93, s91, 0
	s_add_i32 s29, 0, 0x10000
	s_cmp_eq_u32 s45, s92
	s_cselect_b32 s93, s7, s93
	s_cselect_b32 s92, s6, s94
	v_add_u32_e32 v140, s29, v143
	s_cselect_b32 s95, s89, vcc_lo
	s_cselect_b32 s94, s88, s53
	s_add_i32 s12, 0, 0x14000
	ds_read_b128 v[146:149], v140
	ds_read_b128 v[150:153], v140 offset:1024
	ds_read_b128 v[154:157], v140 offset:2048
	ds_read_b128 v[158:161], v140 offset:3072
	v_add_u32_e32 v140, s12, v143
	ds_read_b128 v[170:173], v140
	ds_read_b128 v[174:177], v140 offset:1024
	ds_read_b128 v[196:199], v140 offset:2048
	ds_read_b128 v[200:203], v140 offset:3072
	s_add_i32 m0, s22, 0xc000
	ds_read_b128 v[204:207], v145
	ds_read_b128 v[208:211], v145 offset:1024
	ds_read_b128 v[212:215], v145 offset:2048
	ds_read_b128 v[216:219], v145 offset:3072
	ds_read_b128 v[220:223], v145 offset:4096
	ds_read_b128 v[224:227], v145 offset:5120
	ds_read_b128 v[228:231], v145 offset:6144
	ds_read_b128 v[232:235], v145 offset:7168
	global_load_lds_dwordx4 v136, s[90:91]
	s_add_i32 m0, s22, 0xe000
	s_nop 0
	global_load_lds_dwordx4 v138, s[90:91]
	s_waitcnt vmcnt(8)
	s_waitcnt lgkmcnt(0)
	s_barrier
	s_setprio 1
	s_waitcnt lgkmcnt(0)
	v_mfma_f32_16x16x32_bf16 v[126:129], v[146:149], v[204:207], v[126:129]
	v_mfma_f32_16x16x32_bf16 v[122:125], v[154:157], v[204:207], v[122:125]
	v_mfma_f32_16x16x32_bf16 v[118:121], v[146:149], v[212:215], v[118:121]
	v_mfma_f32_16x16x32_bf16 v[110:113], v[154:157], v[212:215], v[110:113]
	v_mfma_f32_16x16x32_bf16 v[102:105], v[146:149], v[220:223], v[102:105]
	v_mfma_f32_16x16x32_bf16 v[94:97], v[154:157], v[220:223], v[94:97]
	v_mfma_f32_16x16x32_bf16 v[86:89], v[146:149], v[228:231], v[86:89]
	v_mfma_f32_16x16x32_bf16 v[78:81], v[154:157], v[228:231], v[78:81]
	v_mfma_f32_16x16x32_bf16 v[126:129], v[150:153], v[208:211], v[126:129]
	v_mfma_f32_16x16x32_bf16 v[122:125], v[158:161], v[208:211], v[122:125]
	v_mfma_f32_16x16x32_bf16 v[118:121], v[150:153], v[216:219], v[118:121]
	v_mfma_f32_16x16x32_bf16 v[110:113], v[158:161], v[216:219], v[110:113]
	v_mfma_f32_16x16x32_bf16 v[102:105], v[150:153], v[224:227], v[102:105]
	v_mfma_f32_16x16x32_bf16 v[94:97], v[158:161], v[224:227], v[94:97]
	v_mfma_f32_16x16x32_bf16 v[86:89], v[150:153], v[232:235], v[86:89]
	v_mfma_f32_16x16x32_bf16 v[78:81], v[158:161], v[232:235], v[78:81]
	s_setprio 0
	s_setprio 1
	v_mfma_f32_16x16x32_bf16 v[114:117], v[170:173], v[204:207], v[114:117]
	v_mfma_f32_16x16x32_bf16 v[106:109], v[196:199], v[204:207], v[106:109]
	v_mfma_f32_16x16x32_bf16 v[98:101], v[170:173], v[212:215], v[98:101]
	v_mfma_f32_16x16x32_bf16 v[90:93], v[196:199], v[212:215], v[90:93]
	v_mfma_f32_16x16x32_bf16 v[82:85], v[170:173], v[220:223], v[82:85]
	v_mfma_f32_16x16x32_bf16 v[74:77], v[196:199], v[220:223], v[74:77]
	v_mfma_f32_16x16x32_bf16 v[70:73], v[170:173], v[228:231], v[70:73]
	v_mfma_f32_16x16x32_bf16 v[66:69], v[196:199], v[228:231], v[66:69]
	v_mfma_f32_16x16x32_bf16 v[114:117], v[174:177], v[208:211], v[114:117]
	v_mfma_f32_16x16x32_bf16 v[106:109], v[200:203], v[208:211], v[106:109]
	v_mfma_f32_16x16x32_bf16 v[98:101], v[174:177], v[216:219], v[98:101]
	v_mfma_f32_16x16x32_bf16 v[90:93], v[200:203], v[216:219], v[90:93]
	v_mfma_f32_16x16x32_bf16 v[82:85], v[174:177], v[224:227], v[82:85]
	v_mfma_f32_16x16x32_bf16 v[74:77], v[200:203], v[224:227], v[74:77]
	v_mfma_f32_16x16x32_bf16 v[70:73], v[174:177], v[232:235], v[70:73]
	v_mfma_f32_16x16x32_bf16 v[66:69], v[200:203], v[232:235], v[66:69]
	s_setprio 0
	s_barrier
	s_add_i32 s13, s29, s17
	v_lshl_add_u64 v[140:141], s[94:95], 0, v[0:1]
	s_mov_b32 m0, s13
	ds_read_b128 v[204:207], v145 offset:16384
	ds_read_b128 v[208:211], v145 offset:17408
	ds_read_b128 v[212:215], v145 offset:18432
	ds_read_b128 v[216:219], v145 offset:19456
	ds_read_b128 v[220:223], v145 offset:20480
	ds_read_b128 v[224:227], v145 offset:21504
	ds_read_b128 v[228:231], v145 offset:22528
	ds_read_b128 v[232:235], v145 offset:23552
	global_load_lds_dwordx4 v0, s[94:95]
	s_add_i32 m0, s13, 0x2000
	v_lshl_add_u64 v[166:167], s[94:95], 0, v[130:131]
	s_add_u32 s94, s94, s20
	s_addc_u32 s95, s95, 0
	s_add_i32 s12, s12, s17
	global_load_lds_dwordx4 v[166:167], off
	v_lshl_add_u64 v[178:179], s[94:95], 0, v[0:1]
	s_mov_b32 m0, s12
	v_lshl_add_u64 v[188:189], s[94:95], 0, v[130:131]
	global_load_lds_dwordx4 v0, s[94:95]
	s_add_i32 m0, s12, 0x2000
	v_lshl_add_u64 v[190:191], s[92:93], 0, v[134:135]
	global_load_lds_dwordx4 v130, s[94:95]
	s_mov_b32 m0, s22
	v_lshl_add_u64 v[236:237], s[92:93], 0, v[132:133]
	global_load_lds_dwordx4 v134, s[92:93]
	s_mov_b32 m0, s26
	s_nop 0
	global_load_lds_dwordx4 v132, s[92:93]
	s_waitcnt vmcnt(8)
	s_waitcnt lgkmcnt(0)
	s_barrier
; #define PG8_STAGE(bufoff, gbase, voff) do { _Pragma("unroll") for (int _i = 0; _i < 2; ++_i) \
;         __builtin_amdgcn_global_load_lds((const unsigned*)((const char*)(gbase) + (voff)[_i]), (LAS unsigned*)(lds + (bufoff) + ldsw + _i * 8192), 16, 0, 0); } while (0)
; #define PG8_LDA(dst, b, h) do { _Pragma("unroll") for (int m = 0; m < 4; ++m) _Pragma("unroll") for (int k = 0; k < 2; ++k) dst[m][k] = *(const LAS bf16x8*)(lds + PG8_SA(b, h) + aoff + m * 2048 + k * 1024); } while (0)
; #define PG8_LDB(dst, b, h) do { _Pragma("unroll") for (int n = 0; n < 2; ++n) _Pragma("unroll") for (int k = 0; k < 2; ++k) dst[n][k] = *(const LAS bf16x8*)(lds + PG8_SB(b, h) + boff + n * 2048 + k * 1024); } while (0)
; #define PG8_WAIT_V(n) asm volatile("s_waitcnt vmcnt(" #n ")" ::: "memory")
; #define PG8_WAIT_L(n) asm volatile("s_waitcnt lgkmcnt(" #n ")" ::: "memory")
; template <class Epi>
; DI void gemm_phase(LAS unsigned char* lds, int tid, const Gemm g, const Order& S, const Epi& E) {
;     ...
;         for (int t = 0; t < nt; t += 2) {
;             const bool last = (t == nt - 2);
;             const char* a1 = cA + (size_t)(t + 1) * kstep;
;             const char* a2 = last ? nA : cA + (size_t)(t + 2) * kstep; const char* b2 = last ? nB : cB + (size_t)(t + 2) * kstep;
;             const char* a3 = a2 + kstep; const char* b3 = b2 + kstep;
;             PG8_LDB(B0, 0, 0); PG8_LDB(B1, 0, 1); PG8_SCHED; PG8_LDA(At, 0, 0); PG8_STAGE(PG8_SA(1, 1), a1 + hstepA, voffA);
;             PG8_WAIT_V(8); PG8_WAIT_L(0); PG8_BAR; PG8_MMA(0, 0, At, B0); PG8_MMA(0, 1, At, B1); PG8_BAR; PG8_SCHED;
;             PG8_LDA(At, 0, 1); PG8_STAGE(PG8_SB(0, 0), b2, voffB); PG8_STAGE(PG8_SB(0, 1), b2 + hstepB, voffB); PG8_STAGE(PG8_SA(0, 0), a2, voffA);
;             PG8_WAIT_V(8); PG8_WAIT_L(0); PG8_BAR; PG8_MMA(1, 0, At, B0); PG8_MMA(1, 1, At, B1); PG8_BAR; PG8_SCHED;
;             PG8_LDB(B0, 1, 0); PG8_LDB(B1, 1, 1); PG8_SCHED; PG8_LDA(At, 1, 0); PG8_STAGE(PG8_SA(0, 1), a2 + hstepA, voffA);
;             PG8_WAIT_V(8); PG8_WAIT_L(0); PG8_BAR; PG8_MMA(0, 0, At, B0); PG8_MMA(0, 1, At, B1); PG8_BAR; PG8_SCHED;
;             PG8_LDA(At, 1, 1); PG8_STAGE(PG8_SB(1, 0), b3, voffB); PG8_STAGE(PG8_SB(1, 1), b3 + hstepB, voffB); PG8_STAGE(PG8_SA(1, 0), a3, voffA);
;             PG8_WAIT_V(8); PG8_WAIT_L(0); PG8_BAR; PG8_MMA(1, 0, At, B0); PG8_MMA(1, 1, At, B1); PG8_BAR; PG8_SCHED;
	s_setprio 1
	s_waitcnt lgkmcnt(0)
	v_mfma_f32_16x16x32_bf16 v[62:65], v[146:149], v[204:207], v[62:65]
	v_mfma_f32_16x16x32_bf16 v[58:61], v[154:157], v[204:207], v[58:61]
	v_mfma_f32_16x16x32_bf16 v[54:57], v[146:149], v[212:215], v[54:57]
	v_mfma_f32_16x16x32_bf16 v[46:49], v[154:157], v[212:215], v[46:49]
	v_mfma_f32_16x16x32_bf16 v[38:41], v[146:149], v[220:223], v[38:41]
	v_mfma_f32_16x16x32_bf16 v[30:33], v[154:157], v[220:223], v[30:33]
	v_mfma_f32_16x16x32_bf16 v[22:25], v[146:149], v[228:231], v[22:25]
	v_mfma_f32_16x16x32_bf16 v[14:17], v[154:157], v[228:231], v[14:17]
	v_mfma_f32_16x16x32_bf16 v[62:65], v[150:153], v[208:211], v[62:65]
	v_mfma_f32_16x16x32_bf16 v[58:61], v[158:161], v[208:211], v[58:61]
	v_mfma_f32_16x16x32_bf16 v[54:57], v[150:153], v[216:219], v[54:57]
	v_mfma_f32_16x16x32_bf16 v[46:49], v[158:161], v[216:219], v[46:49]
	v_mfma_f32_16x16x32_bf16 v[38:41], v[150:153], v[224:227], v[38:41]
	v_mfma_f32_16x16x32_bf16 v[30:33], v[158:161], v[224:227], v[30:33]
	v_mfma_f32_16x16x32_bf16 v[22:25], v[150:153], v[232:235], v[22:25]
	v_mfma_f32_16x16x32_bf16 v[14:17], v[158:161], v[232:235], v[14:17]
	s_setprio 0
	s_setprio 1
	v_mfma_f32_16x16x32_bf16 v[50:53], v[170:173], v[204:207], v[50:53]
	v_mfma_f32_16x16x32_bf16 v[42:45], v[196:199], v[204:207], v[42:45]
	v_mfma_f32_16x16x32_bf16 v[34:37], v[170:173], v[212:215], v[34:37]
	v_mfma_f32_16x16x32_bf16 v[26:29], v[196:199], v[212:215], v[26:29]
	v_mfma_f32_16x16x32_bf16 v[18:21], v[170:173], v[220:223], v[18:21]
	v_mfma_f32_16x16x32_bf16 v[10:13], v[196:199], v[220:223], v[10:13]
	v_mfma_f32_16x16x32_bf16 v[6:9], v[170:173], v[228:231], v[6:9]
	v_mfma_f32_16x16x32_bf16 v[2:5], v[196:199], v[228:231], v[2:5]
	v_mfma_f32_16x16x32_bf16 v[50:53], v[174:177], v[208:211], v[50:53]
	v_mfma_f32_16x16x32_bf16 v[42:45], v[200:203], v[208:211], v[42:45]
	v_mfma_f32_16x16x32_bf16 v[34:37], v[174:177], v[216:219], v[34:37]
	v_mfma_f32_16x16x32_bf16 v[26:29], v[200:203], v[216:219], v[26:29]
	v_mfma_f32_16x16x32_bf16 v[18:21], v[174:177], v[224:227], v[18:21]
	v_mfma_f32_16x16x32_bf16 v[10:13], v[200:203], v[224:227], v[10:13]
	v_mfma_f32_16x16x32_bf16 v[6:9], v[174:177], v[232:235], v[6:9]
	v_mfma_f32_16x16x32_bf16 v[2:5], v[200:203], v[232:235], v[2:5]
	s_setprio 0
	s_barrier
	s_add_i32 s12, 0, 0x18000
	s_add_i32 s13, 0, 0x1c000
	v_add_u32_e32 v158, s12, v143
	v_add_u32_e32 v165, s13, v143
	ds_read_b128 v[146:149], v158
	ds_read_b128 v[150:153], v158 offset:1024
	ds_read_b128 v[154:157], v158 offset:2048
	ds_read_b128 v[158:161], v158 offset:3072
	ds_read_b128 v[170:173], v165
	ds_read_b128 v[174:177], v165 offset:1024
	ds_read_b128 v[196:199], v165 offset:2048
	ds_read_b128 v[200:203], v165 offset:3072
	s_add_u32 s92, s92, s20
	s_addc_u32 s93, s93, 0
	s_mov_b32 m0, s30
	ds_read_b128 v[204:207], v145 offset:32768
	ds_read_b128 v[208:211], v145 offset:33792
	ds_read_b128 v[212:215], v145 offset:34816
	ds_read_b128 v[216:219], v145 offset:35840
	ds_read_b128 v[220:223], v145 offset:36864
	ds_read_b128 v[224:227], v145 offset:37888
	ds_read_b128 v[228:231], v145 offset:38912
	ds_read_b128 v[232:235], v145 offset:39936
	global_load_lds_dwordx4 v134, s[92:93]
	s_mov_b32 m0, s31
	s_nop 0
	global_load_lds_dwordx4 v132, s[92:93]
	s_waitcnt vmcnt(8)
	s_waitcnt lgkmcnt(0)
	s_barrier
	s_setprio 1
	s_waitcnt lgkmcnt(0)
	v_mfma_f32_16x16x32_bf16 v[126:129], v[146:149], v[204:207], v[126:129]
	v_mfma_f32_16x16x32_bf16 v[122:125], v[154:157], v[204:207], v[122:125]
	v_mfma_f32_16x16x32_bf16 v[118:121], v[146:149], v[212:215], v[118:121]
	v_mfma_f32_16x16x32_bf16 v[110:113], v[154:157], v[212:215], v[110:113]
	v_mfma_f32_16x16x32_bf16 v[102:105], v[146:149], v[220:223], v[102:105]
	v_mfma_f32_16x16x32_bf16 v[94:97], v[154:157], v[220:223], v[94:97]
	v_mfma_f32_16x16x32_bf16 v[86:89], v[146:149], v[228:231], v[86:89]
	v_mfma_f32_16x16x32_bf16 v[78:81], v[154:157], v[228:231], v[78:81]
	v_mfma_f32_16x16x32_bf16 v[126:129], v[150:153], v[208:211], v[126:129]
	v_mfma_f32_16x16x32_bf16 v[122:125], v[158:161], v[208:211], v[122:125]
	v_mfma_f32_16x16x32_bf16 v[118:121], v[150:153], v[216:219], v[118:121]
	v_mfma_f32_16x16x32_bf16 v[110:113], v[158:161], v[216:219], v[110:113]
	v_mfma_f32_16x16x32_bf16 v[102:105], v[150:153], v[224:227], v[102:105]
	v_mfma_f32_16x16x32_bf16 v[94:97], v[158:161], v[224:227], v[94:97]
	v_mfma_f32_16x16x32_bf16 v[86:89], v[150:153], v[232:235], v[86:89]
	v_mfma_f32_16x16x32_bf16 v[78:81], v[158:161], v[232:235], v[78:81]
	s_setprio 0
	s_setprio 1
	v_mfma_f32_16x16x32_bf16 v[114:117], v[170:173], v[204:207], v[114:117]
	v_mfma_f32_16x16x32_bf16 v[106:109], v[196:199], v[204:207], v[106:109]
	v_mfma_f32_16x16x32_bf16 v[98:101], v[170:173], v[212:215], v[98:101]
	v_mfma_f32_16x16x32_bf16 v[90:93], v[196:199], v[212:215], v[90:93]
	v_mfma_f32_16x16x32_bf16 v[82:85], v[170:173], v[220:223], v[82:85]
	v_mfma_f32_16x16x32_bf16 v[74:77], v[196:199], v[220:223], v[74:77]
	v_mfma_f32_16x16x32_bf16 v[70:73], v[170:173], v[228:231], v[70:73]
	v_mfma_f32_16x16x32_bf16 v[66:69], v[196:199], v[228:231], v[66:69]
	v_mfma_f32_16x16x32_bf16 v[114:117], v[174:177], v[208:211], v[114:117]
	v_mfma_f32_16x16x32_bf16 v[106:109], v[200:203], v[208:211], v[106:109]
	v_mfma_f32_16x16x32_bf16 v[98:101], v[174:177], v[216:219], v[98:101]
	v_mfma_f32_16x16x32_bf16 v[90:93], v[200:203], v[216:219], v[90:93]
	v_mfma_f32_16x16x32_bf16 v[82:85], v[174:177], v[224:227], v[82:85]
	v_mfma_f32_16x16x32_bf16 v[74:77], v[200:203], v[224:227], v[74:77]
	v_mfma_f32_16x16x32_bf16 v[70:73], v[174:177], v[232:235], v[70:73]
	v_mfma_f32_16x16x32_bf16 v[66:69], v[200:203], v[232:235], v[66:69]
	s_setprio 0
	s_barrier
; #define PG8_STAGE(bufoff, gbase, voff) do { _Pragma("unroll") for (int _i = 0; _i < 2; ++_i) \
;         __builtin_amdgcn_global_load_lds((const unsigned*)((const char*)(gbase) + (voff)[_i]), (LAS unsigned*)(lds + (bufoff) + ldsw + _i * 8192), 16, 0, 0); } while (0)
; #define PG8_LDA(dst, b, h) do { _Pragma("unroll") for (int m = 0; m < 4; ++m) _Pragma("unroll") for (int k = 0; k < 2; ++k) dst[m][k] = *(const LAS bf16x8*)(lds + PG8_SA(b, h) + aoff + m * 2048 + k * 1024); } while (0)
; #define PG8_LDB(dst, b, h) do { _Pragma("unroll") for (int n = 0; n < 2; ++n) _Pragma("unroll") for (int k = 0; k < 2; ++k) dst[n][k] = *(const LAS bf16x8*)(lds + PG8_SB(b, h) + boff + n * 2048 + k * 1024); } while (0)
; #define PG8_WAIT_V(n) asm volatile("s_waitcnt vmcnt(" #n ")" ::: "memory")
; #define PG8_BAR __builtin_amdgcn_s_barrier()
; template <class Epi>
; DI void gemm_phase(LAS unsigned char* lds, int tid, const Gemm g, const Order& S, const Epi& E) {
;     ...
;         for (int t = 0; t < nt; t += 2) {
;             const bool last = (t == nt - 2);
;             const char* a1 = cA + (size_t)(t + 1) * kstep;
;             const char* a2 = last ? nA : cA + (size_t)(t + 2) * kstep; const char* b2 = last ? nB : cB + (size_t)(t + 2) * kstep;
;             const char* a3 = a2 + kstep; const char* b3 = b2 + kstep;
;             PG8_LDB(B0, 0, 0); PG8_LDB(B1, 0, 1); PG8_SCHED; PG8_LDA(At, 0, 0); PG8_STAGE(PG8_SA(1, 1), a1 + hstepA, voffA);
;             PG8_WAIT_V(8); PG8_WAIT_L(0); PG8_BAR; PG8_MMA(0, 0, At, B0); PG8_MMA(0, 1, At, B1); PG8_BAR; PG8_SCHED;
;             PG8_LDA(At, 0, 1); PG8_STAGE(PG8_SB(0, 0), b2, voffB); PG8_STAGE(PG8_SB(0, 1), b2 + hstepB, voffB); PG8_STAGE(PG8_SA(0, 0), a2, voffA);
;             PG8_WAIT_V(8); PG8_WAIT_L(0); PG8_BAR; PG8_MMA(1, 0, At, B0); PG8_MMA(1, 1, At, B1); PG8_BAR; PG8_SCHED;
;             PG8_LDB(B0, 1, 0); PG8_LDB(B1, 1, 1); PG8_SCHED; PG8_LDA(At, 1, 0); PG8_STAGE(PG8_SA(0, 1), a2 + hstepA, voffA);
;             PG8_WAIT_V(8); PG8_WAIT_L(0); PG8_BAR; PG8_MMA(0, 0, At, B0); PG8_MMA(0, 1, At, B1); PG8_BAR; PG8_SCHED;
;             PG8_LDA(At, 1, 1); PG8_STAGE(PG8_SB(1, 0), b3, voffB); PG8_STAGE(PG8_SB(1, 1), b3 + hstepB, voffB); PG8_STAGE(PG8_SA(1, 0), a3, voffA);
;             PG8_WAIT_V(8); PG8_WAIT_L(0); PG8_BAR; PG8_MMA(1, 0, At, B0); PG8_MMA(1, 1, At, B1); PG8_BAR; PG8_SCHED;
;         }
;         if (wr == 0) PG8_BAR;
	s_add_i32 s12, s12, s17
	v_lshl_add_u64 v[140:141], v[140:141], 0, s[24:25]
	s_mov_b32 m0, s12
	ds_read_b128 v[204:207], v145 offset:49152
	ds_read_b128 v[208:211], v145 offset:50176
	ds_read_b128 v[212:215], v145 offset:51200
	ds_read_b128 v[216:219], v145 offset:52224
	ds_read_b128 v[220:223], v145 offset:53248
	ds_read_b128 v[224:227], v145 offset:54272
	ds_read_b128 v[228:231], v145 offset:55296
	ds_read_b128 v[232:235], v145 offset:56320
	global_load_lds_dwordx4 v[140:141], off
	v_lshl_add_u64 v[140:141], v[166:167], 0, s[24:25]
	s_add_i32 m0, s12, 0x2000
	s_add_i32 s12, s13, s17
	global_load_lds_dwordx4 v[140:141], off
	v_lshl_add_u64 v[140:141], v[178:179], 0, s[24:25]
	s_mov_b32 m0, s12
	s_nop 0
	global_load_lds_dwordx4 v[140:141], off
	v_lshl_add_u64 v[140:141], v[188:189], 0, s[24:25]
	s_add_i32 m0, s12, 0x2000
	s_nop 0
	global_load_lds_dwordx4 v[140:141], off
	v_lshl_add_u64 v[140:141], v[190:191], 0, s[24:25]
	s_mov_b32 m0, s40
	s_nop 0
	global_load_lds_dwordx4 v[140:141], off
	v_lshl_add_u64 v[140:141], v[236:237], 0, s[24:25]
	s_mov_b32 m0, s41
	s_nop 0
	global_load_lds_dwordx4 v[140:141], off
	s_waitcnt vmcnt(8)
	s_waitcnt lgkmcnt(0)
	s_barrier
	s_setprio 1
	s_waitcnt lgkmcnt(0)
	v_mfma_f32_16x16x32_bf16 v[62:65], v[146:149], v[204:207], v[62:65]
	v_mfma_f32_16x16x32_bf16 v[58:61], v[154:157], v[204:207], v[58:61]
	v_mfma_f32_16x16x32_bf16 v[54:57], v[146:149], v[212:215], v[54:57]
	v_mfma_f32_16x16x32_bf16 v[46:49], v[154:157], v[212:215], v[46:49]
	v_mfma_f32_16x16x32_bf16 v[38:41], v[146:149], v[220:223], v[38:41]
	v_mfma_f32_16x16x32_bf16 v[30:33], v[154:157], v[220:223], v[30:33]
	v_mfma_f32_16x16x32_bf16 v[22:25], v[146:149], v[228:231], v[22:25]
	v_mfma_f32_16x16x32_bf16 v[14:17], v[154:157], v[228:231], v[14:17]
	v_mfma_f32_16x16x32_bf16 v[62:65], v[150:153], v[208:211], v[62:65]
	v_mfma_f32_16x16x32_bf16 v[58:61], v[158:161], v[208:211], v[58:61]
	v_mfma_f32_16x16x32_bf16 v[54:57], v[150:153], v[216:219], v[54:57]
	v_mfma_f32_16x16x32_bf16 v[46:49], v[158:161], v[216:219], v[46:49]
	v_mfma_f32_16x16x32_bf16 v[38:41], v[150:153], v[224:227], v[38:41]
	v_mfma_f32_16x16x32_bf16 v[30:33], v[158:161], v[224:227], v[30:33]
	v_mfma_f32_16x16x32_bf16 v[22:25], v[150:153], v[232:235], v[22:25]
	v_mfma_f32_16x16x32_bf16 v[14:17], v[158:161], v[232:235], v[14:17]
	s_setprio 0
	s_setprio 1
	v_mfma_f32_16x16x32_bf16 v[50:53], v[170:173], v[204:207], v[50:53]
	v_mfma_f32_16x16x32_bf16 v[42:45], v[196:199], v[204:207], v[42:45]
	v_mfma_f32_16x16x32_bf16 v[34:37], v[170:173], v[212:215], v[34:37]
	v_mfma_f32_16x16x32_bf16 v[26:29], v[196:199], v[212:215], v[26:29]
	v_mfma_f32_16x16x32_bf16 v[18:21], v[170:173], v[220:223], v[18:21]
	v_mfma_f32_16x16x32_bf16 v[10:13], v[196:199], v[220:223], v[10:13]
	v_mfma_f32_16x16x32_bf16 v[6:9], v[170:173], v[228:231], v[6:9]
	v_mfma_f32_16x16x32_bf16 v[2:5], v[196:199], v[228:231], v[2:5]
	v_mfma_f32_16x16x32_bf16 v[50:53], v[174:177], v[208:211], v[50:53]
	v_mfma_f32_16x16x32_bf16 v[42:45], v[200:203], v[208:211], v[42:45]
	v_mfma_f32_16x16x32_bf16 v[34:37], v[174:177], v[216:219], v[34:37]
	v_mfma_f32_16x16x32_bf16 v[26:29], v[200:203], v[216:219], v[26:29]
	v_mfma_f32_16x16x32_bf16 v[18:21], v[174:177], v[224:227], v[18:21]
	v_mfma_f32_16x16x32_bf16 v[10:13], v[200:203], v[224:227], v[10:13]
	v_mfma_f32_16x16x32_bf16 v[6:9], v[174:177], v[232:235], v[6:9]
	v_mfma_f32_16x16x32_bf16 v[2:5], v[200:203], v[232:235], v[2:5]
	s_setprio 0
	s_barrier
	s_add_u32 s90, s90, 0x100
	s_addc_u32 s91, s91, 0
	s_add_u32 s53, s53, 0x100
	s_addc_u32 vcc_lo, vcc_lo, 0
	s_cmp_ge_u32 vcc_hi, s37
	s_mov_b32 s92, vcc_hi
	s_cbranch_scc0 .LBB0_466
	s_and_b64 vcc, exec, s[86:87]
	s_cbranch_vccz .LBB0_469
	s_barrier

; #define PG8_STAGE(bufoff, gbase, voff) do { _Pragma("unroll") for (int _i = 0; _i < 2; ++_i) \
;         __builtin_amdgcn_global_load_lds((const unsigned*)((const char*)(gbase) + (voff)[_i]), (LAS unsigned*)(lds + (bufoff) + ldsw + _i * 8192), 16, 0, 0); } while (0)
; #define PG8_LDA(dst, b, h) do { _Pragma("unroll") for (int m = 0; m < 4; ++m) _Pragma("unroll") for (int k = 0; k < 2; ++k) dst[m][k] = *(const LAS bf16x8*)(lds + PG8_SA(b, h) + aoff + m * 2048 + k * 1024); } while (0)
; #define PG8_LDB(dst, b, h) do { _Pragma("unroll") for (int n = 0; n < 2; ++n) _Pragma("unroll") for (int k = 0; k < 2; ++k) dst[n][k] = *(const LAS bf16x8*)(lds + PG8_SB(b, h) + boff + n * 2048 + k * 1024); } while (0)
; #define PG8_WAIT_V(n) asm volatile("s_waitcnt vmcnt(" #n ")" ::: "memory")
; #define PG8_WAIT_L(n) asm volatile("s_waitcnt lgkmcnt(" #n ")" ::: "memory")
; template <class Epi>
; DI void gemm_phase(LAS unsigned char* lds, int tid, const Gemm g, const Order& S, const Epi& E) {
;     ...
;         for (int t = 0; t < nt; t += 2) {
;             const bool last = (t == nt - 2);
;             const char* a1 = cA + (size_t)(t + 1) * kstep;
;             const char* a2 = last ? nA : cA + (size_t)(t + 2) * kstep; const char* b2 = last ? nB : cB + (size_t)(t + 2) * kstep;
;             const char* a3 = a2 + kstep; const char* b3 = b2 + kstep;
;             PG8_LDB(B0, 0, 0); PG8_LDB(B1, 0, 1); PG8_SCHED; PG8_LDA(At, 0, 0); PG8_STAGE(PG8_SA(1, 1), a1 + hstepA, voffA);
;             PG8_WAIT_V(8); PG8_WAIT_L(0); PG8_BAR; PG8_MMA(0, 0, At, B0); PG8_MMA(0, 1, At, B1); PG8_BAR; PG8_SCHED;
;             PG8_LDA(At, 0, 1); PG8_STAGE(PG8_SB(0, 0), b2, voffB); PG8_STAGE(PG8_SB(0, 1), b2 + hstepB, voffB); PG8_STAGE(PG8_SA(0, 0), a2, voffA);
;             PG8_WAIT_V(8); PG8_WAIT_L(0); PG8_BAR; PG8_MMA(1, 0, At, B0); PG8_MMA(1, 1, At, B1); PG8_BAR; PG8_SCHED;
;             PG8_LDB(B0, 1, 0); PG8_LDB(B1, 1, 1); PG8_SCHED; PG8_LDA(At, 1, 0); PG8_STAGE(PG8_SA(0, 1), a2 + hstepA, voffA);
;             PG8_WAIT_V(8); PG8_WAIT_L(0); PG8_BAR; PG8_MMA(0, 0, At, B0); PG8_MMA(0, 1, At, B1); PG8_BAR; PG8_SCHED;
;             PG8_LDA(At, 1, 1); PG8_STAGE(PG8_SB(1, 0), b3, voffB); PG8_STAGE(PG8_SB(1, 1), b3 + hstepB, voffB); PG8_STAGE(PG8_SA(1, 0), a3, voffA);
;             PG8_WAIT_V(8); PG8_WAIT_L(0); PG8_BAR; PG8_MMA(1, 0, At, B0); PG8_MMA(1, 1, At, B1); PG8_BAR; PG8_SCHED;
.LBB0_493:
	s_add_i32 s40, s33, 2
	s_add_u32 s41, s84, 0x80
	s_addc_u32 s45, s85, 0
	s_add_i32 s47, 0, 0x10000
	s_cmp_eq_u32 s36, s33
	s_cselect_b32 s87, s7, s45
	s_cselect_b32 s86, s6, s41
	s_cselect_b32 s53, s83, s31
	s_cselect_b32 s52, s82, s30
	s_add_i32 s33, 0, 0x14000
	v_add_u32_e32 v152, s47, v168
	v_add_u32_e32 v160, s33, v168
	ds_read_b128 v[140:143], v152
	ds_read_b128 v[144:147], v152 offset:1024
	ds_read_b128 v[148:151], v152 offset:2048
	ds_read_b128 v[152:155], v152 offset:3072
	ds_read_b128 v[156:159], v160
	ds_read_b128 v[172:175], v160 offset:1024
	ds_read_b128 v[176:179], v160 offset:2048
	ds_read_b128 v[196:199], v160 offset:3072
	s_add_i32 m0, s46, 0xc000
	ds_read_b128 v[200:203], v171
	ds_read_b128 v[204:207], v171 offset:1024
	ds_read_b128 v[208:211], v171 offset:2048
	ds_read_b128 v[212:215], v171 offset:3072
	ds_read_b128 v[216:219], v171 offset:4096
	ds_read_b128 v[220:223], v171 offset:5120
	ds_read_b128 v[224:227], v171 offset:6144
	ds_read_b128 v[228:231], v171 offset:7168
	global_load_lds_dwordx4 v136, s[84:85]
	s_add_i32 m0, s46, 0xe000
	s_nop 0
	global_load_lds_dwordx4 v138, s[84:85]
	s_waitcnt vmcnt(8)
	s_waitcnt lgkmcnt(0)
	s_barrier
	s_setprio 1
	s_waitcnt lgkmcnt(0)
	v_mfma_f32_16x16x32_bf16 v[126:129], v[140:143], v[200:203], v[126:129]
	v_mfma_f32_16x16x32_bf16 v[122:125], v[148:151], v[200:203], v[122:125]
	v_mfma_f32_16x16x32_bf16 v[118:121], v[140:143], v[208:211], v[118:121]
	v_mfma_f32_16x16x32_bf16 v[114:117], v[148:151], v[208:211], v[114:117]
	v_mfma_f32_16x16x32_bf16 v[94:97], v[140:143], v[216:219], v[94:97]
	v_mfma_f32_16x16x32_bf16 v[90:93], v[148:151], v[216:219], v[90:93]
	v_mfma_f32_16x16x32_bf16 v[86:89], v[140:143], v[224:227], v[86:89]
	v_mfma_f32_16x16x32_bf16 v[82:85], v[148:151], v[224:227], v[82:85]
	v_mfma_f32_16x16x32_bf16 v[126:129], v[144:147], v[204:207], v[126:129]
	v_mfma_f32_16x16x32_bf16 v[122:125], v[152:155], v[204:207], v[122:125]
	v_mfma_f32_16x16x32_bf16 v[118:121], v[144:147], v[212:215], v[118:121]
	v_mfma_f32_16x16x32_bf16 v[114:117], v[152:155], v[212:215], v[114:117]
	v_mfma_f32_16x16x32_bf16 v[94:97], v[144:147], v[220:223], v[94:97]
	v_mfma_f32_16x16x32_bf16 v[90:93], v[152:155], v[220:223], v[90:93]
	v_mfma_f32_16x16x32_bf16 v[86:89], v[144:147], v[228:231], v[86:89]
	v_mfma_f32_16x16x32_bf16 v[82:85], v[152:155], v[228:231], v[82:85]
	s_setprio 0
	s_setprio 1
	v_mfma_f32_16x16x32_bf16 v[110:113], v[156:159], v[200:203], v[110:113]
	v_mfma_f32_16x16x32_bf16 v[106:109], v[176:179], v[200:203], v[106:109]
	v_mfma_f32_16x16x32_bf16 v[102:105], v[156:159], v[208:211], v[102:105]
	v_mfma_f32_16x16x32_bf16 v[98:101], v[176:179], v[208:211], v[98:101]
	v_mfma_f32_16x16x32_bf16 v[78:81], v[156:159], v[216:219], v[78:81]
	v_mfma_f32_16x16x32_bf16 v[74:77], v[176:179], v[216:219], v[74:77]
	v_mfma_f32_16x16x32_bf16 v[70:73], v[156:159], v[224:227], v[70:73]
	v_mfma_f32_16x16x32_bf16 v[66:69], v[176:179], v[224:227], v[66:69]
	v_mfma_f32_16x16x32_bf16 v[110:113], v[172:175], v[204:207], v[110:113]
	v_mfma_f32_16x16x32_bf16 v[106:109], v[196:199], v[204:207], v[106:109]
	v_mfma_f32_16x16x32_bf16 v[102:105], v[172:175], v[212:215], v[102:105]
	v_mfma_f32_16x16x32_bf16 v[98:101], v[196:199], v[212:215], v[98:101]
	v_mfma_f32_16x16x32_bf16 v[78:81], v[172:175], v[220:223], v[78:81]
	v_mfma_f32_16x16x32_bf16 v[74:77], v[196:199], v[220:223], v[74:77]
	v_mfma_f32_16x16x32_bf16 v[70:73], v[172:175], v[228:231], v[70:73]
	v_mfma_f32_16x16x32_bf16 v[66:69], v[196:199], v[228:231], v[66:69]
	s_setprio 0
	s_barrier
	s_add_i32 s41, s47, s10
	v_lshl_add_u64 v[160:161], s[52:53], 0, v[0:1]
	s_mov_b32 m0, s41
	ds_read_b128 v[200:203], v171 offset:16384
	ds_read_b128 v[204:207], v171 offset:17408
	ds_read_b128 v[208:211], v171 offset:18432
	ds_read_b128 v[212:215], v171 offset:19456
	ds_read_b128 v[216:219], v171 offset:20480
	ds_read_b128 v[220:223], v171 offset:21504
	ds_read_b128 v[224:227], v171 offset:22528
	ds_read_b128 v[228:231], v171 offset:23552
	global_load_lds_dwordx4 v0, s[52:53]
	s_add_i32 m0, s41, 0x2000
	v_lshl_add_u64 v[166:167], s[52:53], 0, v[130:131]
	s_add_u32 s52, s52, s20
	s_addc_u32 s53, s53, 0
	s_add_i32 s33, s33, s10
	global_load_lds_dwordx4 v[166:167], off
	v_lshl_add_u64 v[188:189], s[52:53], 0, v[0:1]
	s_mov_b32 m0, s33
	v_lshl_add_u64 v[190:191], s[52:53], 0, v[130:131]
	global_load_lds_dwordx4 v0, s[52:53]
	s_add_i32 m0, s33, 0x2000
	v_lshl_add_u64 v[232:233], s[86:87], 0, v[134:135]
	global_load_lds_dwordx4 v130, s[52:53]
	s_mov_b32 m0, s46
	v_lshl_add_u64 v[234:235], s[86:87], 0, v[132:133]
	global_load_lds_dwordx4 v134, s[86:87]
	s_mov_b32 m0, s49
	s_nop 0
	global_load_lds_dwordx4 v132, s[86:87]
	s_waitcnt vmcnt(8)
	s_waitcnt lgkmcnt(0)
	s_barrier
; #define PG8_STAGE(bufoff, gbase, voff) do { _Pragma("unroll") for (int _i = 0; _i < 2; ++_i) \
;         __builtin_amdgcn_global_load_lds((const unsigned*)((const char*)(gbase) + (voff)[_i]), (LAS unsigned*)(lds + (bufoff) + ldsw + _i * 8192), 16, 0, 0); } while (0)
; #define PG8_LDA(dst, b, h) do { _Pragma("unroll") for (int m = 0; m < 4; ++m) _Pragma("unroll") for (int k = 0; k < 2; ++k) dst[m][k] = *(const LAS bf16x8*)(lds + PG8_SA(b, h) + aoff + m * 2048 + k * 1024); } while (0)
; #define PG8_LDB(dst, b, h) do { _Pragma("unroll") for (int n = 0; n < 2; ++n) _Pragma("unroll") for (int k = 0; k < 2; ++k) dst[n][k] = *(const LAS bf16x8*)(lds + PG8_SB(b, h) + boff + n * 2048 + k * 1024); } while (0)
; #define PG8_WAIT_V(n) asm volatile("s_waitcnt vmcnt(" #n ")" ::: "memory")
; #define PG8_WAIT_L(n) asm volatile("s_waitcnt lgkmcnt(" #n ")" ::: "memory")
; template <class Epi>
; DI void gemm_phase(LAS unsigned char* lds, int tid, const Gemm g, const Order& S, const Epi& E) {
;     ...
;         for (int t = 0; t < nt; t += 2) {
;             const bool last = (t == nt - 2);
;             const char* a1 = cA + (size_t)(t + 1) * kstep;
;             const char* a2 = last ? nA : cA + (size_t)(t + 2) * kstep; const char* b2 = last ? nB : cB + (size_t)(t + 2) * kstep;
;             const char* a3 = a2 + kstep; const char* b3 = b2 + kstep;
;             PG8_LDB(B0, 0, 0); PG8_LDB(B1, 0, 1); PG8_SCHED; PG8_LDA(At, 0, 0); PG8_STAGE(PG8_SA(1, 1), a1 + hstepA, voffA);
;             PG8_WAIT_V(8); PG8_WAIT_L(0); PG8_BAR; PG8_MMA(0, 0, At, B0); PG8_MMA(0, 1, At, B1); PG8_BAR; PG8_SCHED;
;             PG8_LDA(At, 0, 1); PG8_STAGE(PG8_SB(0, 0), b2, voffB); PG8_STAGE(PG8_SB(0, 1), b2 + hstepB, voffB); PG8_STAGE(PG8_SA(0, 0), a2, voffA);
;             PG8_WAIT_V(8); PG8_WAIT_L(0); PG8_BAR; PG8_MMA(1, 0, At, B0); PG8_MMA(1, 1, At, B1); PG8_BAR; PG8_SCHED;
;             PG8_LDB(B0, 1, 0); PG8_LDB(B1, 1, 1); PG8_SCHED; PG8_LDA(At, 1, 0); PG8_STAGE(PG8_SA(0, 1), a2 + hstepA, voffA);
;             PG8_WAIT_V(8); PG8_WAIT_L(0); PG8_BAR; PG8_MMA(0, 0, At, B0); PG8_MMA(0, 1, At, B1); PG8_BAR; PG8_SCHED;
;             PG8_LDA(At, 1, 1); PG8_STAGE(PG8_SB(1, 0), b3, voffB); PG8_STAGE(PG8_SB(1, 1), b3 + hstepB, voffB); PG8_STAGE(PG8_SA(1, 0), a3, voffA);
;             PG8_WAIT_V(8); PG8_WAIT_L(0); PG8_BAR; PG8_MMA(1, 0, At, B0); PG8_MMA(1, 1, At, B1); PG8_BAR; PG8_SCHED;
	s_setprio 1
	s_waitcnt lgkmcnt(0)
	v_mfma_f32_16x16x32_bf16 v[62:65], v[140:143], v[200:203], v[62:65]
	v_mfma_f32_16x16x32_bf16 v[58:61], v[148:151], v[200:203], v[58:61]
	v_mfma_f32_16x16x32_bf16 v[54:57], v[140:143], v[208:211], v[54:57]
	v_mfma_f32_16x16x32_bf16 v[50:53], v[148:151], v[208:211], v[50:53]
	v_mfma_f32_16x16x32_bf16 v[30:33], v[140:143], v[216:219], v[30:33]
	v_mfma_f32_16x16x32_bf16 v[26:29], v[148:151], v[216:219], v[26:29]
	v_mfma_f32_16x16x32_bf16 v[22:25], v[140:143], v[224:227], v[22:25]
	v_mfma_f32_16x16x32_bf16 v[18:21], v[148:151], v[224:227], v[18:21]
	v_mfma_f32_16x16x32_bf16 v[62:65], v[144:147], v[204:207], v[62:65]
	v_mfma_f32_16x16x32_bf16 v[58:61], v[152:155], v[204:207], v[58:61]
	v_mfma_f32_16x16x32_bf16 v[54:57], v[144:147], v[212:215], v[54:57]
	v_mfma_f32_16x16x32_bf16 v[50:53], v[152:155], v[212:215], v[50:53]
	v_mfma_f32_16x16x32_bf16 v[30:33], v[144:147], v[220:223], v[30:33]
	v_mfma_f32_16x16x32_bf16 v[26:29], v[152:155], v[220:223], v[26:29]
	v_mfma_f32_16x16x32_bf16 v[22:25], v[144:147], v[228:231], v[22:25]
	v_mfma_f32_16x16x32_bf16 v[18:21], v[152:155], v[228:231], v[18:21]
	s_setprio 0
	s_setprio 1
	v_mfma_f32_16x16x32_bf16 v[46:49], v[156:159], v[200:203], v[46:49]
	v_mfma_f32_16x16x32_bf16 v[42:45], v[176:179], v[200:203], v[42:45]
	v_mfma_f32_16x16x32_bf16 v[38:41], v[156:159], v[208:211], v[38:41]
	v_mfma_f32_16x16x32_bf16 v[34:37], v[176:179], v[208:211], v[34:37]
	v_mfma_f32_16x16x32_bf16 v[14:17], v[156:159], v[216:219], v[14:17]
	v_mfma_f32_16x16x32_bf16 v[10:13], v[176:179], v[216:219], v[10:13]
	v_mfma_f32_16x16x32_bf16 v[6:9], v[156:159], v[224:227], v[6:9]
	v_mfma_f32_16x16x32_bf16 v[2:5], v[176:179], v[224:227], v[2:5]
	v_mfma_f32_16x16x32_bf16 v[46:49], v[172:175], v[204:207], v[46:49]
	v_mfma_f32_16x16x32_bf16 v[42:45], v[196:199], v[204:207], v[42:45]
	v_mfma_f32_16x16x32_bf16 v[38:41], v[172:175], v[212:215], v[38:41]
	v_mfma_f32_16x16x32_bf16 v[34:37], v[196:199], v[212:215], v[34:37]
	v_mfma_f32_16x16x32_bf16 v[14:17], v[172:175], v[220:223], v[14:17]
	v_mfma_f32_16x16x32_bf16 v[10:13], v[196:199], v[220:223], v[10:13]
	v_mfma_f32_16x16x32_bf16 v[6:9], v[172:175], v[228:231], v[6:9]
	v_mfma_f32_16x16x32_bf16 v[2:5], v[196:199], v[228:231], v[2:5]
	s_setprio 0
	s_barrier
	s_add_i32 s33, 0, 0x18000
	s_add_i32 s41, 0, 0x1c000
	v_add_u32_e32 v152, s33, v168
	v_add_u32_e32 v184, s41, v168
	ds_read_b128 v[140:143], v152
	ds_read_b128 v[144:147], v152 offset:1024
	ds_read_b128 v[148:151], v152 offset:2048
	ds_read_b128 v[152:155], v152 offset:3072
	ds_read_b128 v[156:159], v184
	ds_read_b128 v[172:175], v184 offset:1024
	ds_read_b128 v[176:179], v184 offset:2048
	ds_read_b128 v[196:199], v184 offset:3072
	s_add_u32 s52, s86, s20
	s_addc_u32 s53, s87, 0
	s_mov_b32 m0, s92
	ds_read_b128 v[200:203], v171 offset:32768
	ds_read_b128 v[204:207], v171 offset:33792
	ds_read_b128 v[208:211], v171 offset:34816
	ds_read_b128 v[212:215], v171 offset:35840
	ds_read_b128 v[216:219], v171 offset:36864
	ds_read_b128 v[220:223], v171 offset:37888
	ds_read_b128 v[224:227], v171 offset:38912
	ds_read_b128 v[228:231], v171 offset:39936
	global_load_lds_dwordx4 v134, s[52:53]
	s_mov_b32 m0, s93
	s_nop 0
	global_load_lds_dwordx4 v132, s[52:53]
	s_waitcnt vmcnt(8)
	s_waitcnt lgkmcnt(0)
	s_barrier
	s_setprio 1
	s_waitcnt lgkmcnt(0)
	v_mfma_f32_16x16x32_bf16 v[126:129], v[140:143], v[200:203], v[126:129]
	v_mfma_f32_16x16x32_bf16 v[122:125], v[148:151], v[200:203], v[122:125]
	v_mfma_f32_16x16x32_bf16 v[118:121], v[140:143], v[208:211], v[118:121]
	v_mfma_f32_16x16x32_bf16 v[114:117], v[148:151], v[208:211], v[114:117]
	v_mfma_f32_16x16x32_bf16 v[94:97], v[140:143], v[216:219], v[94:97]
	v_mfma_f32_16x16x32_bf16 v[90:93], v[148:151], v[216:219], v[90:93]
	v_mfma_f32_16x16x32_bf16 v[86:89], v[140:143], v[224:227], v[86:89]
	v_mfma_f32_16x16x32_bf16 v[82:85], v[148:151], v[224:227], v[82:85]
	v_mfma_f32_16x16x32_bf16 v[126:129], v[144:147], v[204:207], v[126:129]
	v_mfma_f32_16x16x32_bf16 v[122:125], v[152:155], v[204:207], v[122:125]
	v_mfma_f32_16x16x32_bf16 v[118:121], v[144:147], v[212:215], v[118:121]
	v_mfma_f32_16x16x32_bf16 v[114:117], v[152:155], v[212:215], v[114:117]
	v_mfma_f32_16x16x32_bf16 v[94:97], v[144:147], v[220:223], v[94:97]
	v_mfma_f32_16x16x32_bf16 v[90:93], v[152:155], v[220:223], v[90:93]
	v_mfma_f32_16x16x32_bf16 v[86:89], v[144:147], v[228:231], v[86:89]
	v_mfma_f32_16x16x32_bf16 v[82:85], v[152:155], v[228:231], v[82:85]
	s_setprio 0
	s_setprio 1
	v_mfma_f32_16x16x32_bf16 v[110:113], v[156:159], v[200:203], v[110:113]
	v_mfma_f32_16x16x32_bf16 v[106:109], v[176:179], v[200:203], v[106:109]
	v_mfma_f32_16x16x32_bf16 v[102:105], v[156:159], v[208:211], v[102:105]
	v_mfma_f32_16x16x32_bf16 v[98:101], v[176:179], v[208:211], v[98:101]
	v_mfma_f32_16x16x32_bf16 v[78:81], v[156:159], v[216:219], v[78:81]
	v_mfma_f32_16x16x32_bf16 v[74:77], v[176:179], v[216:219], v[74:77]
	v_mfma_f32_16x16x32_bf16 v[70:73], v[156:159], v[224:227], v[70:73]
	v_mfma_f32_16x16x32_bf16 v[66:69], v[176:179], v[224:227], v[66:69]
	v_mfma_f32_16x16x32_bf16 v[110:113], v[172:175], v[204:207], v[110:113]
	v_mfma_f32_16x16x32_bf16 v[106:109], v[196:199], v[204:207], v[106:109]
	v_mfma_f32_16x16x32_bf16 v[102:105], v[172:175], v[212:215], v[102:105]
	v_mfma_f32_16x16x32_bf16 v[98:101], v[196:199], v[212:215], v[98:101]
	v_mfma_f32_16x16x32_bf16 v[78:81], v[172:175], v[220:223], v[78:81]
	v_mfma_f32_16x16x32_bf16 v[74:77], v[196:199], v[220:223], v[74:77]
	v_mfma_f32_16x16x32_bf16 v[70:73], v[172:175], v[228:231], v[70:73]
	v_mfma_f32_16x16x32_bf16 v[66:69], v[196:199], v[228:231], v[66:69]
	s_setprio 0
	s_barrier
; #define PG8_STAGE(bufoff, gbase, voff) do { _Pragma("unroll") for (int _i = 0; _i < 2; ++_i) \
;         __builtin_amdgcn_global_load_lds((const unsigned*)((const char*)(gbase) + (voff)[_i]), (LAS unsigned*)(lds + (bufoff) + ldsw + _i * 8192), 16, 0, 0); } while (0)
; #define PG8_LDA(dst, b, h) do { _Pragma("unroll") for (int m = 0; m < 4; ++m) _Pragma("unroll") for (int k = 0; k < 2; ++k) dst[m][k] = *(const LAS bf16x8*)(lds + PG8_SA(b, h) + aoff + m * 2048 + k * 1024); } while (0)
; #define PG8_LDB(dst, b, h) do { _Pragma("unroll") for (int n = 0; n < 2; ++n) _Pragma("unroll") for (int k = 0; k < 2; ++k) dst[n][k] = *(const LAS bf16x8*)(lds + PG8_SB(b, h) + boff + n * 2048 + k * 1024); } while (0)
; #define PG8_WAIT_V(n) asm volatile("s_waitcnt vmcnt(" #n ")" ::: "memory")
; #define PG8_BAR __builtin_amdgcn_s_barrier()
; template <class Epi>
; DI void gemm_phase(LAS unsigned char* lds, int tid, const Gemm g, const Order& S, const Epi& E) {
;     ...
;         for (int t = 0; t < nt; t += 2) {
;             const bool last = (t == nt - 2);
;             const char* a1 = cA + (size_t)(t + 1) * kstep;
;             const char* a2 = last ? nA : cA + (size_t)(t + 2) * kstep; const char* b2 = last ? nB : cB + (size_t)(t + 2) * kstep;
;             const char* a3 = a2 + kstep; const char* b3 = b2 + kstep;
;             PG8_LDB(B0, 0, 0); PG8_LDB(B1, 0, 1); PG8_SCHED; PG8_LDA(At, 0, 0); PG8_STAGE(PG8_SA(1, 1), a1 + hstepA, voffA);
;             PG8_WAIT_V(8); PG8_WAIT_L(0); PG8_BAR; PG8_MMA(0, 0, At, B0); PG8_MMA(0, 1, At, B1); PG8_BAR; PG8_SCHED;
;             PG8_LDA(At, 0, 1); PG8_STAGE(PG8_SB(0, 0), b2, voffB); PG8_STAGE(PG8_SB(0, 1), b2 + hstepB, voffB); PG8_STAGE(PG8_SA(0, 0), a2, voffA);
;             PG8_WAIT_V(8); PG8_WAIT_L(0); PG8_BAR; PG8_MMA(1, 0, At, B0); PG8_MMA(1, 1, At, B1); PG8_BAR; PG8_SCHED;
;             PG8_LDB(B0, 1, 0); PG8_LDB(B1, 1, 1); PG8_SCHED; PG8_LDA(At, 1, 0); PG8_STAGE(PG8_SA(0, 1), a2 + hstepA, voffA);
;             PG8_WAIT_V(8); PG8_WAIT_L(0); PG8_BAR; PG8_MMA(0, 0, At, B0); PG8_MMA(0, 1, At, B1); PG8_BAR; PG8_SCHED;
;             PG8_LDA(At, 1, 1); PG8_STAGE(PG8_SB(1, 0), b3, voffB); PG8_STAGE(PG8_SB(1, 1), b3 + hstepB, voffB); PG8_STAGE(PG8_SA(1, 0), a3, voffA);
;             PG8_WAIT_V(8); PG8_WAIT_L(0); PG8_BAR; PG8_MMA(1, 0, At, B0); PG8_MMA(1, 1, At, B1); PG8_BAR; PG8_SCHED;
;         }
;         if (wr == 0) PG8_BAR;
	s_add_i32 s33, s33, s10
	v_lshl_add_u64 v[160:161], v[160:161], 0, s[24:25]
	s_mov_b32 m0, s33
	ds_read_b128 v[200:203], v171 offset:49152
	ds_read_b128 v[204:207], v171 offset:50176
	ds_read_b128 v[208:211], v171 offset:51200
	ds_read_b128 v[212:215], v171 offset:52224
	ds_read_b128 v[216:219], v171 offset:53248
	ds_read_b128 v[220:223], v171 offset:54272
	ds_read_b128 v[224:227], v171 offset:55296
	ds_read_b128 v[228:231], v171 offset:56320
	global_load_lds_dwordx4 v[160:161], off
	v_lshl_add_u64 v[160:161], v[166:167], 0, s[24:25]
	s_add_i32 m0, s33, 0x2000
	s_add_i32 s33, s41, s10
	global_load_lds_dwordx4 v[160:161], off
	v_lshl_add_u64 v[160:161], v[188:189], 0, s[24:25]
	s_mov_b32 m0, s33
	s_nop 0
	global_load_lds_dwordx4 v[160:161], off
	v_lshl_add_u64 v[160:161], v[190:191], 0, s[24:25]
	s_add_i32 m0, s33, 0x2000
	s_nop 0
	global_load_lds_dwordx4 v[160:161], off
	v_lshl_add_u64 v[160:161], v[232:233], 0, s[24:25]
	s_mov_b32 m0, s37
	s_nop 0
	global_load_lds_dwordx4 v[160:161], off
	v_lshl_add_u64 v[160:161], v[234:235], 0, s[24:25]
	s_mov_b32 m0, s39
	s_nop 0
	global_load_lds_dwordx4 v[160:161], off
	s_waitcnt vmcnt(8)
	s_waitcnt lgkmcnt(0)
	s_barrier
	s_setprio 1
	s_waitcnt lgkmcnt(0)
	v_mfma_f32_16x16x32_bf16 v[62:65], v[140:143], v[200:203], v[62:65]
	v_mfma_f32_16x16x32_bf16 v[58:61], v[148:151], v[200:203], v[58:61]
	v_mfma_f32_16x16x32_bf16 v[54:57], v[140:143], v[208:211], v[54:57]
	v_mfma_f32_16x16x32_bf16 v[50:53], v[148:151], v[208:211], v[50:53]
	v_mfma_f32_16x16x32_bf16 v[30:33], v[140:143], v[216:219], v[30:33]
	v_mfma_f32_16x16x32_bf16 v[26:29], v[148:151], v[216:219], v[26:29]
	v_mfma_f32_16x16x32_bf16 v[22:25], v[140:143], v[224:227], v[22:25]
	v_mfma_f32_16x16x32_bf16 v[18:21], v[148:151], v[224:227], v[18:21]
	v_mfma_f32_16x16x32_bf16 v[62:65], v[144:147], v[204:207], v[62:65]
	v_mfma_f32_16x16x32_bf16 v[58:61], v[152:155], v[204:207], v[58:61]
	v_mfma_f32_16x16x32_bf16 v[54:57], v[144:147], v[212:215], v[54:57]
	v_mfma_f32_16x16x32_bf16 v[50:53], v[152:155], v[212:215], v[50:53]
	v_mfma_f32_16x16x32_bf16 v[30:33], v[144:147], v[220:223], v[30:33]
	v_mfma_f32_16x16x32_bf16 v[26:29], v[152:155], v[220:223], v[26:29]
	v_mfma_f32_16x16x32_bf16 v[22:25], v[144:147], v[228:231], v[22:25]
	v_mfma_f32_16x16x32_bf16 v[18:21], v[152:155], v[228:231], v[18:21]
	s_setprio 0
	s_setprio 1
	v_mfma_f32_16x16x32_bf16 v[46:49], v[156:159], v[200:203], v[46:49]
	v_mfma_f32_16x16x32_bf16 v[42:45], v[176:179], v[200:203], v[42:45]
	v_mfma_f32_16x16x32_bf16 v[38:41], v[156:159], v[208:211], v[38:41]
	v_mfma_f32_16x16x32_bf16 v[34:37], v[176:179], v[208:211], v[34:37]
	v_mfma_f32_16x16x32_bf16 v[14:17], v[156:159], v[216:219], v[14:17]
	v_mfma_f32_16x16x32_bf16 v[10:13], v[176:179], v[216:219], v[10:13]
	v_mfma_f32_16x16x32_bf16 v[6:9], v[156:159], v[224:227], v[6:9]
	v_mfma_f32_16x16x32_bf16 v[2:5], v[176:179], v[224:227], v[2:5]
	v_mfma_f32_16x16x32_bf16 v[46:49], v[172:175], v[204:207], v[46:49]
	v_mfma_f32_16x16x32_bf16 v[42:45], v[196:199], v[204:207], v[42:45]
	v_mfma_f32_16x16x32_bf16 v[38:41], v[172:175], v[212:215], v[38:41]
	v_mfma_f32_16x16x32_bf16 v[34:37], v[196:199], v[212:215], v[34:37]
	v_mfma_f32_16x16x32_bf16 v[14:17], v[172:175], v[220:223], v[14:17]
	v_mfma_f32_16x16x32_bf16 v[10:13], v[196:199], v[220:223], v[10:13]
	v_mfma_f32_16x16x32_bf16 v[6:9], v[172:175], v[228:231], v[6:9]
	v_mfma_f32_16x16x32_bf16 v[2:5], v[196:199], v[228:231], v[2:5]
	s_setprio 0
	s_barrier
	s_add_u32 s84, s84, 0x100
	s_addc_u32 s85, s85, 0
	s_add_u32 s30, s30, 0x100
	s_addc_u32 s31, s31, 0
	s_cmp_ge_u32 s40, s28
	s_mov_b32 s33, s40
	s_cbranch_scc0 .LBB0_493
	s_and_b64 vcc, exec, s[80:81]
	s_cbranch_vccz .LBB0_496
	s_barrier

; #define PG8_STAGE(bufoff, gbase, voff) do { _Pragma("unroll") for (int _i = 0; _i < 2; ++_i) \
;         __builtin_amdgcn_global_load_lds((const unsigned*)((const char*)(gbase) + (voff)[_i]), (LAS unsigned*)(lds + (bufoff) + ldsw + _i * 8192), 16, 0, 0); } while (0)
; #define PG8_LDA(dst, b, h) do { _Pragma("unroll") for (int m = 0; m < 4; ++m) _Pragma("unroll") for (int k = 0; k < 2; ++k) dst[m][k] = *(const LAS bf16x8*)(lds + PG8_SA(b, h) + aoff + m * 2048 + k * 1024); } while (0)
; #define PG8_LDB(dst, b, h) do { _Pragma("unroll") for (int n = 0; n < 2; ++n) _Pragma("unroll") for (int k = 0; k < 2; ++k) dst[n][k] = *(const LAS bf16x8*)(lds + PG8_SB(b, h) + boff + n * 2048 + k * 1024); } while (0)
; #define PG8_WAIT_V(n) asm volatile("s_waitcnt vmcnt(" #n ")" ::: "memory")
; #define PG8_WAIT_L(n) asm volatile("s_waitcnt lgkmcnt(" #n ")" ::: "memory")
; template <class Epi>
; DI void gemm_phase(LAS unsigned char* lds, int tid, const Gemm g, const Order& S, const Epi& E) {
;     ...
;         for (int t = 0; t < nt; t += 2) {
;             const bool last = (t == nt - 2);
;             const char* a1 = cA + (size_t)(t + 1) * kstep;
;             const char* a2 = last ? nA : cA + (size_t)(t + 2) * kstep; const char* b2 = last ? nB : cB + (size_t)(t + 2) * kstep;
;             const char* a3 = a2 + kstep; const char* b3 = b2 + kstep;
;             PG8_LDB(B0, 0, 0); PG8_LDB(B1, 0, 1); PG8_SCHED; PG8_LDA(At, 0, 0); PG8_STAGE(PG8_SA(1, 1), a1 + hstepA, voffA);
;             PG8_WAIT_V(8); PG8_WAIT_L(0); PG8_BAR; PG8_MMA(0, 0, At, B0); PG8_MMA(0, 1, At, B1); PG8_BAR; PG8_SCHED;
;             PG8_LDA(At, 0, 1); PG8_STAGE(PG8_SB(0, 0), b2, voffB); PG8_STAGE(PG8_SB(0, 1), b2 + hstepB, voffB); PG8_STAGE(PG8_SA(0, 0), a2, voffA);
;             PG8_WAIT_V(8); PG8_WAIT_L(0); PG8_BAR; PG8_MMA(1, 0, At, B0); PG8_MMA(1, 1, At, B1); PG8_BAR; PG8_SCHED;
;             PG8_LDB(B0, 1, 0); PG8_LDB(B1, 1, 1); PG8_SCHED; PG8_LDA(At, 1, 0); PG8_STAGE(PG8_SA(0, 1), a2 + hstepA, voffA);
;             PG8_WAIT_V(8); PG8_WAIT_L(0); PG8_BAR; PG8_MMA(0, 0, At, B0); PG8_MMA(0, 1, At, B1); PG8_BAR; PG8_SCHED;
;             PG8_LDA(At, 1, 1); PG8_STAGE(PG8_SB(1, 0), b3, voffB); PG8_STAGE(PG8_SB(1, 1), b3 + hstepB, voffB); PG8_STAGE(PG8_SA(1, 0), a3, voffA);
;             PG8_WAIT_V(8); PG8_WAIT_L(0); PG8_BAR; PG8_MMA(1, 0, At, B0); PG8_MMA(1, 1, At, B1); PG8_BAR; PG8_SCHED;
.LBB0_513:
	s_add_u32 s48, s74, 0xfffc0080
	s_addc_u32 s49, s75, -1
	s_add_i32 s51, 0, 0x10000
	s_cmp_eq_u32 s47, 12
	s_cselect_b32 s79, s39, s49
	s_cselect_b32 s78, s40, s48
	s_cselect_b32 s77, s41, s46
	s_cselect_b32 s76, s43, s45
	s_add_i32 s52, 0, 0x14000
	v_add_u32_e32 v156, s51, v145
	v_add_u32_e32 v160, s52, v145
	ds_read_b128 v[140:143], v156
	ds_read_b128 v[148:151], v156 offset:1024
	ds_read_b128 v[152:155], v156 offset:2048
	ds_read_b128 v[156:159], v156 offset:3072
	ds_read_b128 v[164:167], v160
	ds_read_b128 v[170:173], v160 offset:1024
	ds_read_b128 v[174:177], v160 offset:2048
	ds_read_b128 v[196:199], v160 offset:3072
	s_add_i32 m0, s22, 0xc000
	ds_read_b128 v[200:203], v147
	ds_read_b128 v[204:207], v147 offset:1024
	ds_read_b128 v[208:211], v147 offset:2048
	ds_read_b128 v[212:215], v147 offset:3072
	ds_read_b128 v[216:219], v147 offset:4096
	ds_read_b128 v[220:223], v147 offset:5120
	ds_read_b128 v[224:227], v147 offset:6144
	ds_read_b128 v[228:231], v147 offset:7168
	global_load_lds_dwordx4 v136, s[74:75]
	s_add_i32 m0, s22, 0xe000
	s_nop 0
	global_load_lds_dwordx4 v138, s[74:75]
	s_waitcnt vmcnt(8)
	s_waitcnt lgkmcnt(0)
	s_barrier
	s_setprio 1
	s_waitcnt lgkmcnt(0)
	v_mfma_f32_16x16x32_bf16 v[126:129], v[140:143], v[200:203], v[126:129]
	v_mfma_f32_16x16x32_bf16 v[122:125], v[152:155], v[200:203], v[122:125]
	v_mfma_f32_16x16x32_bf16 v[110:113], v[140:143], v[208:211], v[110:113]
	v_mfma_f32_16x16x32_bf16 v[106:109], v[152:155], v[208:211], v[106:109]
	v_mfma_f32_16x16x32_bf16 v[94:97], v[140:143], v[216:219], v[94:97]
	v_mfma_f32_16x16x32_bf16 v[90:93], v[152:155], v[216:219], v[90:93]
	v_mfma_f32_16x16x32_bf16 v[78:81], v[140:143], v[224:227], v[78:81]
	v_mfma_f32_16x16x32_bf16 v[74:77], v[152:155], v[224:227], v[74:77]
	v_mfma_f32_16x16x32_bf16 v[126:129], v[148:151], v[204:207], v[126:129]
	v_mfma_f32_16x16x32_bf16 v[122:125], v[156:159], v[204:207], v[122:125]
	v_mfma_f32_16x16x32_bf16 v[110:113], v[148:151], v[212:215], v[110:113]
	v_mfma_f32_16x16x32_bf16 v[106:109], v[156:159], v[212:215], v[106:109]
	v_mfma_f32_16x16x32_bf16 v[94:97], v[148:151], v[220:223], v[94:97]
	v_mfma_f32_16x16x32_bf16 v[90:93], v[156:159], v[220:223], v[90:93]
	v_mfma_f32_16x16x32_bf16 v[78:81], v[148:151], v[228:231], v[78:81]
	v_mfma_f32_16x16x32_bf16 v[74:77], v[156:159], v[228:231], v[74:77]
	s_setprio 0
	s_setprio 1
	v_mfma_f32_16x16x32_bf16 v[118:121], v[164:167], v[200:203], v[118:121]
	v_mfma_f32_16x16x32_bf16 v[114:117], v[174:177], v[200:203], v[114:117]
	v_mfma_f32_16x16x32_bf16 v[102:105], v[164:167], v[208:211], v[102:105]
	v_mfma_f32_16x16x32_bf16 v[98:101], v[174:177], v[208:211], v[98:101]
	v_mfma_f32_16x16x32_bf16 v[86:89], v[164:167], v[216:219], v[86:89]
	v_mfma_f32_16x16x32_bf16 v[82:85], v[174:177], v[216:219], v[82:85]
	v_mfma_f32_16x16x32_bf16 v[70:73], v[164:167], v[224:227], v[70:73]
	v_mfma_f32_16x16x32_bf16 v[66:69], v[174:177], v[224:227], v[66:69]
	v_mfma_f32_16x16x32_bf16 v[118:121], v[170:173], v[204:207], v[118:121]
	v_mfma_f32_16x16x32_bf16 v[114:117], v[196:199], v[204:207], v[114:117]
	v_mfma_f32_16x16x32_bf16 v[102:105], v[170:173], v[212:215], v[102:105]
	v_mfma_f32_16x16x32_bf16 v[98:101], v[196:199], v[212:215], v[98:101]
	v_mfma_f32_16x16x32_bf16 v[86:89], v[170:173], v[220:223], v[86:89]
	v_mfma_f32_16x16x32_bf16 v[82:85], v[196:199], v[220:223], v[82:85]
	v_mfma_f32_16x16x32_bf16 v[70:73], v[170:173], v[228:231], v[70:73]
	v_mfma_f32_16x16x32_bf16 v[66:69], v[196:199], v[228:231], v[66:69]
	s_setprio 0
	s_barrier
	s_add_i32 s48, s51, s17
	v_lshl_add_u64 v[160:161], s[76:77], 0, v[0:1]
	s_mov_b32 m0, s48
	ds_read_b128 v[200:203], v147 offset:16384
	ds_read_b128 v[204:207], v147 offset:17408
	ds_read_b128 v[208:211], v147 offset:18432
	ds_read_b128 v[212:215], v147 offset:19456
	ds_read_b128 v[216:219], v147 offset:20480
	ds_read_b128 v[220:223], v147 offset:21504
	ds_read_b128 v[224:227], v147 offset:22528
	ds_read_b128 v[228:231], v147 offset:23552
	global_load_lds_dwordx4 v0, s[76:77]
	s_add_i32 m0, s48, 0x2000
	s_add_u32 s48, s76, 0x40000
	v_lshl_add_u64 v[178:179], s[76:77], 0, v[134:135]
	s_addc_u32 s49, s77, 0
	s_add_i32 s51, s52, s17
	global_load_lds_dwordx4 v134, s[76:77]
	s_mov_b32 m0, s51
	v_lshl_add_u64 v[190:191], s[78:79], 0, v[132:133]
	global_load_lds_dwordx4 v0, s[48:49]
	s_add_i32 m0, s51, 0x2000
	s_nop 0
	global_load_lds_dwordx4 v134, s[48:49]
	v_lshl_add_u64 v[188:189], s[78:79], 0, v[130:131]
	s_mov_b32 m0, s22
	s_nop 0
	global_load_lds_dwordx4 v130, s[78:79]
	s_mov_b32 m0, s26
	s_nop 0
	global_load_lds_dwordx4 v132, s[78:79]
	s_waitcnt vmcnt(8)
	s_waitcnt lgkmcnt(0)
	s_barrier
; #define PG8_STAGE(bufoff, gbase, voff) do { _Pragma("unroll") for (int _i = 0; _i < 2; ++_i) \
;         __builtin_amdgcn_global_load_lds((const unsigned*)((const char*)(gbase) + (voff)[_i]), (LAS unsigned*)(lds + (bufoff) + ldsw + _i * 8192), 16, 0, 0); } while (0)
; #define PG8_LDA(dst, b, h) do { _Pragma("unroll") for (int m = 0; m < 4; ++m) _Pragma("unroll") for (int k = 0; k < 2; ++k) dst[m][k] = *(const LAS bf16x8*)(lds + PG8_SA(b, h) + aoff + m * 2048 + k * 1024); } while (0)
; #define PG8_LDB(dst, b, h) do { _Pragma("unroll") for (int n = 0; n < 2; ++n) _Pragma("unroll") for (int k = 0; k < 2; ++k) dst[n][k] = *(const LAS bf16x8*)(lds + PG8_SB(b, h) + boff + n * 2048 + k * 1024); } while (0)
; #define PG8_WAIT_V(n) asm volatile("s_waitcnt vmcnt(" #n ")" ::: "memory")
; #define PG8_WAIT_L(n) asm volatile("s_waitcnt lgkmcnt(" #n ")" ::: "memory")
; template <class Epi>
; DI void gemm_phase(LAS unsigned char* lds, int tid, const Gemm g, const Order& S, const Epi& E) {
;     ...
;         for (int t = 0; t < nt; t += 2) {
;             const bool last = (t == nt - 2);
;             const char* a1 = cA + (size_t)(t + 1) * kstep;
;             const char* a2 = last ? nA : cA + (size_t)(t + 2) * kstep; const char* b2 = last ? nB : cB + (size_t)(t + 2) * kstep;
;             const char* a3 = a2 + kstep; const char* b3 = b2 + kstep;
;             PG8_LDB(B0, 0, 0); PG8_LDB(B1, 0, 1); PG8_SCHED; PG8_LDA(At, 0, 0); PG8_STAGE(PG8_SA(1, 1), a1 + hstepA, voffA);
;             PG8_WAIT_V(8); PG8_WAIT_L(0); PG8_BAR; PG8_MMA(0, 0, At, B0); PG8_MMA(0, 1, At, B1); PG8_BAR; PG8_SCHED;
;             PG8_LDA(At, 0, 1); PG8_STAGE(PG8_SB(0, 0), b2, voffB); PG8_STAGE(PG8_SB(0, 1), b2 + hstepB, voffB); PG8_STAGE(PG8_SA(0, 0), a2, voffA);
;             PG8_WAIT_V(8); PG8_WAIT_L(0); PG8_BAR; PG8_MMA(1, 0, At, B0); PG8_MMA(1, 1, At, B1); PG8_BAR; PG8_SCHED;
;             PG8_LDB(B0, 1, 0); PG8_LDB(B1, 1, 1); PG8_SCHED; PG8_LDA(At, 1, 0); PG8_STAGE(PG8_SA(0, 1), a2 + hstepA, voffA);
;             PG8_WAIT_V(8); PG8_WAIT_L(0); PG8_BAR; PG8_MMA(0, 0, At, B0); PG8_MMA(0, 1, At, B1); PG8_BAR; PG8_SCHED;
;             PG8_LDA(At, 1, 1); PG8_STAGE(PG8_SB(1, 0), b3, voffB); PG8_STAGE(PG8_SB(1, 1), b3 + hstepB, voffB); PG8_STAGE(PG8_SA(1, 0), a3, voffA);
;             PG8_WAIT_V(8); PG8_WAIT_L(0); PG8_BAR; PG8_MMA(1, 0, At, B0); PG8_MMA(1, 1, At, B1); PG8_BAR; PG8_SCHED;
	s_setprio 1
	s_waitcnt lgkmcnt(0)
	v_mfma_f32_16x16x32_bf16 v[62:65], v[140:143], v[200:203], v[62:65]
	v_mfma_f32_16x16x32_bf16 v[58:61], v[152:155], v[200:203], v[58:61]
	v_mfma_f32_16x16x32_bf16 v[46:49], v[140:143], v[208:211], v[46:49]
	v_mfma_f32_16x16x32_bf16 v[42:45], v[152:155], v[208:211], v[42:45]
	v_mfma_f32_16x16x32_bf16 v[30:33], v[140:143], v[216:219], v[30:33]
	v_mfma_f32_16x16x32_bf16 v[26:29], v[152:155], v[216:219], v[26:29]
	v_mfma_f32_16x16x32_bf16 v[14:17], v[140:143], v[224:227], v[14:17]
	v_mfma_f32_16x16x32_bf16 v[10:13], v[152:155], v[224:227], v[10:13]
	v_mfma_f32_16x16x32_bf16 v[62:65], v[148:151], v[204:207], v[62:65]
	v_mfma_f32_16x16x32_bf16 v[58:61], v[156:159], v[204:207], v[58:61]
	v_mfma_f32_16x16x32_bf16 v[46:49], v[148:151], v[212:215], v[46:49]
	v_mfma_f32_16x16x32_bf16 v[42:45], v[156:159], v[212:215], v[42:45]
	v_mfma_f32_16x16x32_bf16 v[30:33], v[148:151], v[220:223], v[30:33]
	v_mfma_f32_16x16x32_bf16 v[26:29], v[156:159], v[220:223], v[26:29]
	v_mfma_f32_16x16x32_bf16 v[14:17], v[148:151], v[228:231], v[14:17]
	v_mfma_f32_16x16x32_bf16 v[10:13], v[156:159], v[228:231], v[10:13]
	s_setprio 0
	s_setprio 1
	v_mfma_f32_16x16x32_bf16 v[54:57], v[164:167], v[200:203], v[54:57]
	v_mfma_f32_16x16x32_bf16 v[50:53], v[174:177], v[200:203], v[50:53]
	v_mfma_f32_16x16x32_bf16 v[38:41], v[164:167], v[208:211], v[38:41]
	v_mfma_f32_16x16x32_bf16 v[34:37], v[174:177], v[208:211], v[34:37]
	v_mfma_f32_16x16x32_bf16 v[22:25], v[164:167], v[216:219], v[22:25]
	v_mfma_f32_16x16x32_bf16 v[18:21], v[174:177], v[216:219], v[18:21]
	v_mfma_f32_16x16x32_bf16 v[6:9], v[164:167], v[224:227], v[6:9]
	v_mfma_f32_16x16x32_bf16 v[2:5], v[174:177], v[224:227], v[2:5]
	v_mfma_f32_16x16x32_bf16 v[54:57], v[170:173], v[204:207], v[54:57]
	v_mfma_f32_16x16x32_bf16 v[50:53], v[196:199], v[204:207], v[50:53]
	v_mfma_f32_16x16x32_bf16 v[38:41], v[170:173], v[212:215], v[38:41]
	v_mfma_f32_16x16x32_bf16 v[34:37], v[196:199], v[212:215], v[34:37]
	v_mfma_f32_16x16x32_bf16 v[22:25], v[170:173], v[220:223], v[22:25]
	v_mfma_f32_16x16x32_bf16 v[18:21], v[196:199], v[220:223], v[18:21]
	v_mfma_f32_16x16x32_bf16 v[6:9], v[170:173], v[228:231], v[6:9]
	v_mfma_f32_16x16x32_bf16 v[2:5], v[196:199], v[228:231], v[2:5]
	s_setprio 0
	s_barrier
	s_add_i32 s51, 0, 0x18000
	s_add_i32 s52, 0, 0x1c000
	v_add_u32_e32 v156, s51, v145
	v_add_u32_e32 v168, s52, v145
	ds_read_b128 v[140:143], v156
	ds_read_b128 v[148:151], v156 offset:1024
	ds_read_b128 v[152:155], v156 offset:2048
	ds_read_b128 v[156:159], v156 offset:3072
	ds_read_b128 v[164:167], v168
	ds_read_b128 v[170:173], v168 offset:1024
	ds_read_b128 v[174:177], v168 offset:2048
	ds_read_b128 v[196:199], v168 offset:3072
	s_add_u32 s48, s78, 0x40000
	s_addc_u32 s49, s79, 0
	s_mov_b32 m0, s28
	ds_read_b128 v[200:203], v147 offset:32768
	ds_read_b128 v[204:207], v147 offset:33792
	ds_read_b128 v[208:211], v147 offset:34816
	ds_read_b128 v[212:215], v147 offset:35840
	ds_read_b128 v[216:219], v147 offset:36864
	ds_read_b128 v[220:223], v147 offset:37888
	ds_read_b128 v[224:227], v147 offset:38912
	ds_read_b128 v[228:231], v147 offset:39936
	global_load_lds_dwordx4 v130, s[48:49]
	s_mov_b32 m0, s30
	s_nop 0
	global_load_lds_dwordx4 v132, s[48:49]
	s_waitcnt vmcnt(8)
	s_waitcnt lgkmcnt(0)
	s_barrier
	s_setprio 1
	s_waitcnt lgkmcnt(0)
	v_mfma_f32_16x16x32_bf16 v[126:129], v[140:143], v[200:203], v[126:129]
	v_mfma_f32_16x16x32_bf16 v[122:125], v[152:155], v[200:203], v[122:125]
	v_mfma_f32_16x16x32_bf16 v[110:113], v[140:143], v[208:211], v[110:113]
	v_mfma_f32_16x16x32_bf16 v[106:109], v[152:155], v[208:211], v[106:109]
	v_mfma_f32_16x16x32_bf16 v[94:97], v[140:143], v[216:219], v[94:97]
	v_mfma_f32_16x16x32_bf16 v[90:93], v[152:155], v[216:219], v[90:93]
	v_mfma_f32_16x16x32_bf16 v[78:81], v[140:143], v[224:227], v[78:81]
	v_mfma_f32_16x16x32_bf16 v[74:77], v[152:155], v[224:227], v[74:77]
	v_mfma_f32_16x16x32_bf16 v[126:129], v[148:151], v[204:207], v[126:129]
	v_mfma_f32_16x16x32_bf16 v[122:125], v[156:159], v[204:207], v[122:125]
	v_mfma_f32_16x16x32_bf16 v[110:113], v[148:151], v[212:215], v[110:113]
	v_mfma_f32_16x16x32_bf16 v[106:109], v[156:159], v[212:215], v[106:109]
	v_mfma_f32_16x16x32_bf16 v[94:97], v[148:151], v[220:223], v[94:97]
	v_mfma_f32_16x16x32_bf16 v[90:93], v[156:159], v[220:223], v[90:93]
	v_mfma_f32_16x16x32_bf16 v[78:81], v[148:151], v[228:231], v[78:81]
	v_mfma_f32_16x16x32_bf16 v[74:77], v[156:159], v[228:231], v[74:77]
	s_setprio 0
	s_setprio 1
	v_mfma_f32_16x16x32_bf16 v[118:121], v[164:167], v[200:203], v[118:121]
	v_mfma_f32_16x16x32_bf16 v[114:117], v[174:177], v[200:203], v[114:117]
	v_mfma_f32_16x16x32_bf16 v[102:105], v[164:167], v[208:211], v[102:105]
	v_mfma_f32_16x16x32_bf16 v[98:101], v[174:177], v[208:211], v[98:101]
	v_mfma_f32_16x16x32_bf16 v[86:89], v[164:167], v[216:219], v[86:89]
	v_mfma_f32_16x16x32_bf16 v[82:85], v[174:177], v[216:219], v[82:85]
	v_mfma_f32_16x16x32_bf16 v[70:73], v[164:167], v[224:227], v[70:73]
	v_mfma_f32_16x16x32_bf16 v[66:69], v[174:177], v[224:227], v[66:69]
	v_mfma_f32_16x16x32_bf16 v[118:121], v[170:173], v[204:207], v[118:121]
	v_mfma_f32_16x16x32_bf16 v[114:117], v[196:199], v[204:207], v[114:117]
	v_mfma_f32_16x16x32_bf16 v[102:105], v[170:173], v[212:215], v[102:105]
	v_mfma_f32_16x16x32_bf16 v[98:101], v[196:199], v[212:215], v[98:101]
	v_mfma_f32_16x16x32_bf16 v[86:89], v[170:173], v[220:223], v[86:89]
	v_mfma_f32_16x16x32_bf16 v[82:85], v[196:199], v[220:223], v[82:85]
	v_mfma_f32_16x16x32_bf16 v[70:73], v[170:173], v[228:231], v[70:73]
	v_mfma_f32_16x16x32_bf16 v[66:69], v[196:199], v[228:231], v[66:69]
	s_setprio 0
	s_barrier
; #define PG8_STAGE(bufoff, gbase, voff) do { _Pragma("unroll") for (int _i = 0; _i < 2; ++_i) \
;         __builtin_amdgcn_global_load_lds((const unsigned*)((const char*)(gbase) + (voff)[_i]), (LAS unsigned*)(lds + (bufoff) + ldsw + _i * 8192), 16, 0, 0); } while (0)
; #define PG8_LDA(dst, b, h) do { _Pragma("unroll") for (int m = 0; m < 4; ++m) _Pragma("unroll") for (int k = 0; k < 2; ++k) dst[m][k] = *(const LAS bf16x8*)(lds + PG8_SA(b, h) + aoff + m * 2048 + k * 1024); } while (0)
; #define PG8_LDB(dst, b, h) do { _Pragma("unroll") for (int n = 0; n < 2; ++n) _Pragma("unroll") for (int k = 0; k < 2; ++k) dst[n][k] = *(const LAS bf16x8*)(lds + PG8_SB(b, h) + boff + n * 2048 + k * 1024); } while (0)
; #define PG8_WAIT_V(n) asm volatile("s_waitcnt vmcnt(" #n ")" ::: "memory")
; #define PG8_BAR __builtin_amdgcn_s_barrier()
; template <class Epi>
; DI void gemm_phase(LAS unsigned char* lds, int tid, const Gemm g, const Order& S, const Epi& E) {
;     ...
;         for (int t = 0; t < nt; t += 2) {
;             const bool last = (t == nt - 2);
;             const char* a1 = cA + (size_t)(t + 1) * kstep;
;             const char* a2 = last ? nA : cA + (size_t)(t + 2) * kstep; const char* b2 = last ? nB : cB + (size_t)(t + 2) * kstep;
;             const char* a3 = a2 + kstep; const char* b3 = b2 + kstep;
;             PG8_LDB(B0, 0, 0); PG8_LDB(B1, 0, 1); PG8_SCHED; PG8_LDA(At, 0, 0); PG8_STAGE(PG8_SA(1, 1), a1 + hstepA, voffA);
;             PG8_WAIT_V(8); PG8_WAIT_L(0); PG8_BAR; PG8_MMA(0, 0, At, B0); PG8_MMA(0, 1, At, B1); PG8_BAR; PG8_SCHED;
;             PG8_LDA(At, 0, 1); PG8_STAGE(PG8_SB(0, 0), b2, voffB); PG8_STAGE(PG8_SB(0, 1), b2 + hstepB, voffB); PG8_STAGE(PG8_SA(0, 0), a2, voffA);
;             PG8_WAIT_V(8); PG8_WAIT_L(0); PG8_BAR; PG8_MMA(1, 0, At, B0); PG8_MMA(1, 1, At, B1); PG8_BAR; PG8_SCHED;
;             PG8_LDB(B0, 1, 0); PG8_LDB(B1, 1, 1); PG8_SCHED; PG8_LDA(At, 1, 0); PG8_STAGE(PG8_SA(0, 1), a2 + hstepA, voffA);
;             PG8_WAIT_V(8); PG8_WAIT_L(0); PG8_BAR; PG8_MMA(0, 0, At, B0); PG8_MMA(0, 1, At, B1); PG8_BAR; PG8_SCHED;
;             PG8_LDA(At, 1, 1); PG8_STAGE(PG8_SB(1, 0), b3, voffB); PG8_STAGE(PG8_SB(1, 1), b3 + hstepB, voffB); PG8_STAGE(PG8_SA(1, 0), a3, voffA);
;             PG8_WAIT_V(8); PG8_WAIT_L(0); PG8_BAR; PG8_MMA(1, 0, At, B0); PG8_MMA(1, 1, At, B1); PG8_BAR; PG8_SCHED;
;         }
;         if (wr == 0) PG8_BAR;
	s_add_i32 s48, s51, s17
	v_lshl_add_u64 v[160:161], v[160:161], 0, s[24:25]
	s_mov_b32 m0, s48
	ds_read_b128 v[200:203], v147 offset:49152
	ds_read_b128 v[204:207], v147 offset:50176
	ds_read_b128 v[208:211], v147 offset:51200
	ds_read_b128 v[212:215], v147 offset:52224
	ds_read_b128 v[216:219], v147 offset:53248
	ds_read_b128 v[220:223], v147 offset:54272
	ds_read_b128 v[224:227], v147 offset:55296
	ds_read_b128 v[228:231], v147 offset:56320
	global_load_lds_dwordx4 v[160:161], off
	s_add_i32 m0, s48, 0x2000
	s_add_u32 s48, s76, 0x40080
	v_lshl_add_u64 v[160:161], v[178:179], 0, s[24:25]
	s_addc_u32 s49, s77, 0
	s_add_i32 s51, s52, s17
	global_load_lds_dwordx4 v[160:161], off
	s_mov_b32 m0, s51
	s_nop 0
	global_load_lds_dwordx4 v0, s[48:49]
	s_add_i32 m0, s51, 0x2000
	s_nop 0
	global_load_lds_dwordx4 v134, s[48:49]
	v_lshl_add_u64 v[160:161], v[188:189], 0, s[24:25]
	s_mov_b32 m0, s34
	s_nop 0
	global_load_lds_dwordx4 v[160:161], off
	v_lshl_add_u64 v[160:161], v[190:191], 0, s[24:25]
	s_mov_b32 m0, s36
	s_nop 0
	global_load_lds_dwordx4 v[160:161], off
	s_waitcnt vmcnt(8)
	s_waitcnt lgkmcnt(0)
	s_barrier
	s_setprio 1
	s_waitcnt lgkmcnt(0)
	v_mfma_f32_16x16x32_bf16 v[62:65], v[140:143], v[200:203], v[62:65]
	v_mfma_f32_16x16x32_bf16 v[58:61], v[152:155], v[200:203], v[58:61]
	v_mfma_f32_16x16x32_bf16 v[46:49], v[140:143], v[208:211], v[46:49]
	v_mfma_f32_16x16x32_bf16 v[42:45], v[152:155], v[208:211], v[42:45]
	v_mfma_f32_16x16x32_bf16 v[30:33], v[140:143], v[216:219], v[30:33]
	v_mfma_f32_16x16x32_bf16 v[26:29], v[152:155], v[216:219], v[26:29]
	v_mfma_f32_16x16x32_bf16 v[14:17], v[140:143], v[224:227], v[14:17]
	v_mfma_f32_16x16x32_bf16 v[10:13], v[152:155], v[224:227], v[10:13]
	v_mfma_f32_16x16x32_bf16 v[62:65], v[148:151], v[204:207], v[62:65]
	v_mfma_f32_16x16x32_bf16 v[58:61], v[156:159], v[204:207], v[58:61]
	v_mfma_f32_16x16x32_bf16 v[46:49], v[148:151], v[212:215], v[46:49]
	v_mfma_f32_16x16x32_bf16 v[42:45], v[156:159], v[212:215], v[42:45]
	v_mfma_f32_16x16x32_bf16 v[30:33], v[148:151], v[220:223], v[30:33]
	v_mfma_f32_16x16x32_bf16 v[26:29], v[156:159], v[220:223], v[26:29]
	v_mfma_f32_16x16x32_bf16 v[14:17], v[148:151], v[228:231], v[14:17]
	v_mfma_f32_16x16x32_bf16 v[10:13], v[156:159], v[228:231], v[10:13]
	s_setprio 0
	s_setprio 1
	v_mfma_f32_16x16x32_bf16 v[54:57], v[164:167], v[200:203], v[54:57]
	v_mfma_f32_16x16x32_bf16 v[50:53], v[174:177], v[200:203], v[50:53]
	v_mfma_f32_16x16x32_bf16 v[38:41], v[164:167], v[208:211], v[38:41]
	v_mfma_f32_16x16x32_bf16 v[34:37], v[174:177], v[208:211], v[34:37]
	v_mfma_f32_16x16x32_bf16 v[22:25], v[164:167], v[216:219], v[22:25]
	v_mfma_f32_16x16x32_bf16 v[18:21], v[174:177], v[216:219], v[18:21]
	v_mfma_f32_16x16x32_bf16 v[6:9], v[164:167], v[224:227], v[6:9]
	v_mfma_f32_16x16x32_bf16 v[2:5], v[174:177], v[224:227], v[2:5]
	v_mfma_f32_16x16x32_bf16 v[54:57], v[170:173], v[204:207], v[54:57]
	v_mfma_f32_16x16x32_bf16 v[50:53], v[196:199], v[204:207], v[50:53]
	v_mfma_f32_16x16x32_bf16 v[38:41], v[170:173], v[212:215], v[38:41]
	v_mfma_f32_16x16x32_bf16 v[34:37], v[196:199], v[212:215], v[34:37]
	v_mfma_f32_16x16x32_bf16 v[22:25], v[170:173], v[220:223], v[22:25]
	v_mfma_f32_16x16x32_bf16 v[18:21], v[196:199], v[220:223], v[18:21]
	v_mfma_f32_16x16x32_bf16 v[6:9], v[170:173], v[228:231], v[6:9]
	v_mfma_f32_16x16x32_bf16 v[2:5], v[196:199], v[228:231], v[2:5]
	s_setprio 0
	s_barrier
	s_add_i32 s47, s47, 2
	s_add_u32 s74, s74, 0x100
	s_addc_u32 s75, s75, 0
	s_add_u32 s45, s45, 0x100
	s_addc_u32 s46, s46, 0
	s_cmp_gt_u32 s47, 13
	s_cbranch_scc0 .LBB0_513
	s_and_b64 vcc, exec, s[8:9]
	s_cbranch_vccz .LBB0_516
	s_barrier
